# hand-written epilogue paths also for the K and V column tile (rotary / scale, f32 cache rows), unreachable compiler epilogue deleted
# baseline (speedup 1.0000x reference)
; __device__ __forceinline__ void xcd_barrier(const XcdBarrier& b) {
;     ...
;     }
;     __syncthreads();
; }
; __global__ void __launch_bounds__(512, 2) fwd(Args a) {
;     ...
;     for (int L = 0; L < DEPTH; ++L) {
.LBB0_234:
	s_or_b64 exec, exec, s[4:5]
	s_add_i32 s96, s96, 1
	s_cmp_eq_u32 s96, 4
	s_waitcnt lgkmcnt(0)
	s_barrier
	s_cbranch_scc1 .LBB0_928
	s_nop 0
	s_nop 0

; #define PG8_STAGE(bufoff, gbase, voff) do { _Pragma("unroll") for (int _i = 0; _i < 2; ++_i) \
;         __builtin_amdgcn_global_load_lds((const unsigned*)((const char*)(gbase) + (voff)[_i]), (PG8_LAS unsigned*)(lds + (bufoff) + ldsw + _i * 8192), 16, 0, 0); } while (0)
; #define PG8_LDA(dst, b, h) do { _Pragma("unroll") for (int m = 0; m < 4; ++m) _Pragma("unroll") for (int k = 0; k < 2; ++k) dst[m][k] = *(const PG8_LAS bf16x8*)(lds + PG8_SA(b, h) + aoff + m * 2048 + k * 1024); } while (0)
; #define PG8_LDB(dst, b, h) do { _Pragma("unroll") for (int n = 0; n < 2; ++n) _Pragma("unroll") for (int k = 0; k < 2; ++k) dst[n][k] = *(const PG8_LAS bf16x8*)(lds + PG8_SB(b, h) + boff + n * 2048 + k * 1024); } while (0)
; #define PG8_MMA(ai, bj, At, Bt) do { __builtin_amdgcn_s_setprio(1); _Pragma("unroll") for (int m = 0; m < 4; ++m) _Pragma("unroll") for (int n = 0; n < 2; ++n) _Pragma("unroll") for (int k = 0; k < 2; ++k) \
;         acc[ai][bj][m][n] = __builtin_amdgcn_mfma_f32_16x16x32_bf16(Bt[n][k], At[m][k], acc[ai][bj][m][n], 0, 0, 0); __builtin_amdgcn_s_setprio(0); } while (0)
; #define PG8_WAIT_V(n) asm volatile("s_waitcnt vmcnt(" #n ")" ::: "memory")
; #define PG8_WAIT_L(n) asm volatile("s_waitcnt lgkmcnt(" #n ")" ::: "memory")
; #define PG8_BAR __builtin_amdgcn_s_barrier()
; #define PG8_SCHED __builtin_amdgcn_sched_barrier(0)
; template <class Epi, class Sched, bool ALIGN_EPI = false, bool SP2 = false>
; __device__ __forceinline__ void gemm_phase(PG8_LAS unsigned char* lds, const Gemm g, const Sched& S, const Epi& E, const int w0) {
;     ...
;             PG8_LDB(B0, 0, 0); PG8_LDB(B1, 0, 1); PG8_SCHED; PG8_LDA(At, 0, 0); PG8_STAGE(PG8_SA(1, 1), a1 + hstep, voffA);
;             PG8_WAIT_V(8); PG8_WAIT_L(0); PG8_BAR; PG8_MMA(0, 0, At, B0); PG8_MMA(0, 1, At, B1); PG8_BAR; PG8_SCHED;
;             PG8_LDA(At, 0, 1); PG8_STAGE(PG8_SB(0, 0), b2, voffB); PG8_STAGE(PG8_SB(0, 1), b2 + hstep, voffB); PG8_STAGE(PG8_SA(0, 0), a2, voffA);
;             PG8_WAIT_V(8); PG8_WAIT_L(0); PG8_BAR; PG8_MMA(1, 0, At, B0); PG8_MMA(1, 1, At, B1); PG8_BAR; PG8_SCHED;
.LBB0_277:
	s_add_u32 s10, s8, 0xfffc0080
	s_addc_u32 s11, s9, -1
	s_add_i32 s28, 0, 0x10000
	s_cmp_eq_u32 s20, 12
	s_cselect_b32 s13, s5, s11
	s_cselect_b32 s12, s7, s10
	s_cselect_b32 s11, s16, s19
	s_cselect_b32 s10, s17, s18
	s_add_i32 s30, 0, 0x14000
	v_add_u32_e32 v108, s28, v247
	v_add_u32_e32 v156, s30, v247
	ds_read_b128 v[96:99], v108
	ds_read_b128 v[100:103], v108 offset:1024
	ds_read_b128 v[104:107], v108 offset:2048
	ds_read_b128 v[108:111], v108 offset:3072
	ds_read_b128 v[144:147], v156
	ds_read_b128 v[148:151], v156 offset:1024
	ds_read_b128 v[152:155], v156 offset:2048
	ds_read_b128 v[156:159], v156 offset:3072
	v_lshl_add_u64 v[210:211], s[8:9], 0, v[206:207]
	s_add_i32 m0, s59, 0xc000
	ds_read_b128 v[160:163], v249
	ds_read_b128 v[164:167], v249 offset:1024
	ds_read_b128 v[168:171], v249 offset:2048
	ds_read_b128 v[172:175], v249 offset:3072
	ds_read_b128 v[176:179], v249 offset:4096
	ds_read_b128 v[180:183], v249 offset:5120
	ds_read_b128 v[184:187], v249 offset:6144
	ds_read_b128 v[188:191], v249 offset:7168
	global_load_lds_dwordx4 v[210:211], off
	v_lshl_add_u64 v[210:211], s[8:9], 0, v[208:209]
	s_add_i32 m0, s59, 0xe000
	s_nop 0
	global_load_lds_dwordx4 v[210:211], off
	s_waitcnt vmcnt(8)
	s_waitcnt lgkmcnt(0)
	s_barrier
	s_setprio 1
	s_waitcnt lgkmcnt(0)
	v_mfma_f32_16x16x32_bf16 v[132:135], v[96:99], v[160:163], v[132:135]
	v_mfma_f32_16x16x32_bf16 v[128:131], v[104:107], v[160:163], v[128:131]
	v_mfma_f32_16x16x32_bf16 v[140:143], v[96:99], v[168:171], v[140:143]
	v_mfma_f32_16x16x32_bf16 v[136:139], v[104:107], v[168:171], v[136:139]
	v_mfma_f32_16x16x32_bf16 v[92:95], v[96:99], v[176:179], v[92:95]
	v_mfma_f32_16x16x32_bf16 v[88:91], v[104:107], v[176:179], v[88:91]
	v_mfma_f32_16x16x32_bf16 v[76:79], v[96:99], v[184:187], v[76:79]
	v_mfma_f32_16x16x32_bf16 v[72:75], v[104:107], v[184:187], v[72:75]
	v_mfma_f32_16x16x32_bf16 v[132:135], v[100:103], v[164:167], v[132:135]
	v_mfma_f32_16x16x32_bf16 v[128:131], v[108:111], v[164:167], v[128:131]
	v_mfma_f32_16x16x32_bf16 v[140:143], v[100:103], v[172:175], v[140:143]
	v_mfma_f32_16x16x32_bf16 v[136:139], v[108:111], v[172:175], v[136:139]
	v_mfma_f32_16x16x32_bf16 v[92:95], v[100:103], v[180:183], v[92:95]
	v_mfma_f32_16x16x32_bf16 v[88:91], v[108:111], v[180:183], v[88:91]
	v_mfma_f32_16x16x32_bf16 v[76:79], v[100:103], v[188:191], v[76:79]
	v_mfma_f32_16x16x32_bf16 v[72:75], v[108:111], v[188:191], v[72:75]
	s_setprio 0
	s_setprio 1
	v_mfma_f32_16x16x32_bf16 v[116:119], v[144:147], v[160:163], v[116:119]
	v_mfma_f32_16x16x32_bf16 v[112:115], v[152:155], v[160:163], v[112:115]
	v_mfma_f32_16x16x32_bf16 v[124:127], v[144:147], v[168:171], v[124:127]
	v_mfma_f32_16x16x32_bf16 v[120:123], v[152:155], v[168:171], v[120:123]
	v_mfma_f32_16x16x32_bf16 v[84:87], v[144:147], v[176:179], v[84:87]
	v_mfma_f32_16x16x32_bf16 v[80:83], v[152:155], v[176:179], v[80:83]
	v_mfma_f32_16x16x32_bf16 v[68:71], v[144:147], v[184:187], v[68:71]
	v_mfma_f32_16x16x32_bf16 v[64:67], v[152:155], v[184:187], v[64:67]
	v_mfma_f32_16x16x32_bf16 v[116:119], v[148:151], v[164:167], v[116:119]
	v_mfma_f32_16x16x32_bf16 v[112:115], v[156:159], v[164:167], v[112:115]
	v_mfma_f32_16x16x32_bf16 v[124:127], v[148:151], v[172:175], v[124:127]
	v_mfma_f32_16x16x32_bf16 v[120:123], v[156:159], v[172:175], v[120:123]
	v_mfma_f32_16x16x32_bf16 v[84:87], v[148:151], v[180:183], v[84:87]
	v_mfma_f32_16x16x32_bf16 v[80:83], v[156:159], v[180:183], v[80:83]
	v_mfma_f32_16x16x32_bf16 v[68:71], v[148:151], v[188:191], v[68:71]
	v_mfma_f32_16x16x32_bf16 v[64:67], v[156:159], v[188:191], v[64:67]
	s_setprio 0
	s_barrier
	s_add_i32 s28, s28, s55
	v_lshl_add_u64 v[210:211], s[10:11], 0, v[200:201]
	s_mov_b32 m0, s28
	ds_read_b128 v[160:163], v249 offset:16384
	ds_read_b128 v[164:167], v249 offset:17408
	ds_read_b128 v[168:171], v249 offset:18432
	ds_read_b128 v[172:175], v249 offset:19456
	ds_read_b128 v[176:179], v249 offset:20480
	ds_read_b128 v[180:183], v249 offset:21504
	ds_read_b128 v[184:187], v249 offset:22528
	ds_read_b128 v[188:191], v249 offset:23552
	global_load_lds_dwordx4 v[210:211], off
	s_add_i32 m0, s28, 0x2000
	s_add_u32 s28, s10, 0x40000
	v_lshl_add_u64 v[212:213], s[10:11], 0, v[204:205]
	s_addc_u32 s29, s11, 0
	s_add_i32 s30, s30, s55
	global_load_lds_dwordx4 v[212:213], off
	v_lshl_add_u64 v[214:215], s[28:29], 0, v[200:201]
	s_mov_b32 m0, s30
	v_lshl_add_u64 v[216:217], s[12:13], 0, v[202:203]
	global_load_lds_dwordx4 v[214:215], off
	v_lshl_add_u64 v[214:215], s[28:29], 0, v[204:205]
	s_add_i32 m0, s30, 0x2000
	s_nop 0
	global_load_lds_dwordx4 v[214:215], off
	v_lshl_add_u64 v[214:215], s[12:13], 0, v[198:199]
	s_mov_b32 m0, s59
	s_nop 0
	global_load_lds_dwordx4 v[214:215], off
	s_mov_b32 m0, s86
	s_nop 0
	global_load_lds_dwordx4 v[216:217], off
	s_waitcnt vmcnt(8)
	s_waitcnt lgkmcnt(0)
	s_barrier
; #define PG8_STAGE(bufoff, gbase, voff) do { _Pragma("unroll") for (int _i = 0; _i < 2; ++_i) \
;         __builtin_amdgcn_global_load_lds((const unsigned*)((const char*)(gbase) + (voff)[_i]), (PG8_LAS unsigned*)(lds + (bufoff) + ldsw + _i * 8192), 16, 0, 0); } while (0)
; #define PG8_LDA(dst, b, h) do { _Pragma("unroll") for (int m = 0; m < 4; ++m) _Pragma("unroll") for (int k = 0; k < 2; ++k) dst[m][k] = *(const PG8_LAS bf16x8*)(lds + PG8_SA(b, h) + aoff + m * 2048 + k * 1024); } while (0)
; #define PG8_LDB(dst, b, h) do { _Pragma("unroll") for (int n = 0; n < 2; ++n) _Pragma("unroll") for (int k = 0; k < 2; ++k) dst[n][k] = *(const PG8_LAS bf16x8*)(lds + PG8_SB(b, h) + boff + n * 2048 + k * 1024); } while (0)
; #define PG8_MMA(ai, bj, At, Bt) do { __builtin_amdgcn_s_setprio(1); _Pragma("unroll") for (int m = 0; m < 4; ++m) _Pragma("unroll") for (int n = 0; n < 2; ++n) _Pragma("unroll") for (int k = 0; k < 2; ++k) \
;         acc[ai][bj][m][n] = __builtin_amdgcn_mfma_f32_16x16x32_bf16(Bt[n][k], At[m][k], acc[ai][bj][m][n], 0, 0, 0); __builtin_amdgcn_s_setprio(0); } while (0)
; #define PG8_WAIT_V(n) asm volatile("s_waitcnt vmcnt(" #n ")" ::: "memory")
; #define PG8_WAIT_L(n) asm volatile("s_waitcnt lgkmcnt(" #n ")" ::: "memory")
; #define PG8_BAR __builtin_amdgcn_s_barrier()
; #define PG8_SCHED __builtin_amdgcn_sched_barrier(0)
; template <class Epi, class Sched, bool ALIGN_EPI = false, bool SP2 = false>
; __device__ __forceinline__ void gemm_phase(PG8_LAS unsigned char* lds, const Gemm g, const Sched& S, const Epi& E, const int w0) {
;     ...
;             PG8_WAIT_V(8); PG8_WAIT_L(0); PG8_BAR; PG8_MMA(1, 0, At, B0); PG8_MMA(1, 1, At, B1); PG8_BAR; PG8_SCHED;
;             PG8_LDB(B0, 1, 0); PG8_LDB(B1, 1, 1); PG8_SCHED; PG8_LDA(At, 1, 0); PG8_STAGE(PG8_SA(0, 1), a2 + hstep, voffA);
;             PG8_WAIT_V(8); PG8_WAIT_L(0); PG8_BAR; PG8_MMA(0, 0, At, B0); PG8_MMA(0, 1, At, B1); PG8_BAR; PG8_SCHED;
	s_setprio 1
	s_waitcnt lgkmcnt(0)
	v_mfma_f32_16x16x32_bf16 v[60:63], v[96:99], v[160:163], v[60:63]
	v_mfma_f32_16x16x32_bf16 v[56:59], v[104:107], v[160:163], v[56:59]
	v_mfma_f32_16x16x32_bf16 v[44:47], v[96:99], v[168:171], v[44:47]
	v_mfma_f32_16x16x32_bf16 v[40:43], v[104:107], v[168:171], v[40:43]
	v_mfma_f32_16x16x32_bf16 v[28:31], v[96:99], v[176:179], v[28:31]
	v_mfma_f32_16x16x32_bf16 v[24:27], v[104:107], v[176:179], v[24:27]
	v_mfma_f32_16x16x32_bf16 v[12:15], v[96:99], v[184:187], v[12:15]
	v_mfma_f32_16x16x32_bf16 v[8:11], v[104:107], v[184:187], v[8:11]
	v_mfma_f32_16x16x32_bf16 v[60:63], v[100:103], v[164:167], v[60:63]
	v_mfma_f32_16x16x32_bf16 v[56:59], v[108:111], v[164:167], v[56:59]
	v_mfma_f32_16x16x32_bf16 v[44:47], v[100:103], v[172:175], v[44:47]
	v_mfma_f32_16x16x32_bf16 v[40:43], v[108:111], v[172:175], v[40:43]
	v_mfma_f32_16x16x32_bf16 v[28:31], v[100:103], v[180:183], v[28:31]
	v_mfma_f32_16x16x32_bf16 v[24:27], v[108:111], v[180:183], v[24:27]
	v_mfma_f32_16x16x32_bf16 v[12:15], v[100:103], v[188:191], v[12:15]
	v_mfma_f32_16x16x32_bf16 v[8:11], v[108:111], v[188:191], v[8:11]
	s_setprio 0
	s_setprio 1
	v_mfma_f32_16x16x32_bf16 v[52:55], v[144:147], v[160:163], v[52:55]
	v_mfma_f32_16x16x32_bf16 v[48:51], v[152:155], v[160:163], v[48:51]
	v_mfma_f32_16x16x32_bf16 v[36:39], v[144:147], v[168:171], v[36:39]
	v_mfma_f32_16x16x32_bf16 v[32:35], v[152:155], v[168:171], v[32:35]
	v_mfma_f32_16x16x32_bf16 v[20:23], v[144:147], v[176:179], v[20:23]
	v_mfma_f32_16x16x32_bf16 v[16:19], v[152:155], v[176:179], v[16:19]
	v_mfma_f32_16x16x32_bf16 v[4:7], v[144:147], v[184:187], v[4:7]
	v_mfma_f32_16x16x32_bf16 v[0:3], v[152:155], v[184:187], v[0:3]
	v_mfma_f32_16x16x32_bf16 v[52:55], v[148:151], v[164:167], v[52:55]
	v_mfma_f32_16x16x32_bf16 v[48:51], v[156:159], v[164:167], v[48:51]
	v_mfma_f32_16x16x32_bf16 v[36:39], v[148:151], v[172:175], v[36:39]
	v_mfma_f32_16x16x32_bf16 v[32:35], v[156:159], v[172:175], v[32:35]
	v_mfma_f32_16x16x32_bf16 v[20:23], v[148:151], v[180:183], v[20:23]
	v_mfma_f32_16x16x32_bf16 v[16:19], v[156:159], v[180:183], v[16:19]
	v_mfma_f32_16x16x32_bf16 v[4:7], v[148:151], v[188:191], v[4:7]
	v_mfma_f32_16x16x32_bf16 v[0:3], v[156:159], v[188:191], v[0:3]
	s_setprio 0
	s_barrier
	s_add_i32 s28, 0, 0x18000
	s_add_i32 s29, 0, 0x1c000
	v_add_u32_e32 v108, s28, v247
	v_add_u32_e32 v156, s29, v247
	ds_read_b128 v[96:99], v108
	ds_read_b128 v[100:103], v108 offset:1024
	ds_read_b128 v[104:107], v108 offset:2048
	ds_read_b128 v[108:111], v108 offset:3072
	ds_read_b128 v[144:147], v156
	ds_read_b128 v[148:151], v156 offset:1024
	ds_read_b128 v[152:155], v156 offset:2048
	ds_read_b128 v[156:159], v156 offset:3072
	s_add_u32 s12, s12, 0x40000
	s_addc_u32 s13, s13, 0
	s_mov_b32 m0, s87
	v_lshl_add_u64 v[218:219], s[12:13], 0, v[198:199]
	ds_read_b128 v[160:163], v249 offset:32768
	ds_read_b128 v[164:167], v249 offset:33792
	ds_read_b128 v[168:171], v249 offset:34816
	ds_read_b128 v[172:175], v249 offset:35840
	ds_read_b128 v[176:179], v249 offset:36864
	ds_read_b128 v[180:183], v249 offset:37888
	ds_read_b128 v[184:187], v249 offset:38912
	ds_read_b128 v[188:191], v249 offset:39936
	global_load_lds_dwordx4 v[218:219], off
	v_lshl_add_u64 v[218:219], s[12:13], 0, v[202:203]
	s_mov_b32 m0, s88
	s_nop 0
	global_load_lds_dwordx4 v[218:219], off
	s_waitcnt vmcnt(8)
	s_waitcnt lgkmcnt(0)
	s_barrier
	s_setprio 1
	s_waitcnt lgkmcnt(0)
	v_mfma_f32_16x16x32_bf16 v[132:135], v[96:99], v[160:163], v[132:135]
	v_mfma_f32_16x16x32_bf16 v[128:131], v[104:107], v[160:163], v[128:131]
	v_mfma_f32_16x16x32_bf16 v[140:143], v[96:99], v[168:171], v[140:143]
	v_mfma_f32_16x16x32_bf16 v[136:139], v[104:107], v[168:171], v[136:139]
	v_mfma_f32_16x16x32_bf16 v[92:95], v[96:99], v[176:179], v[92:95]
	v_mfma_f32_16x16x32_bf16 v[88:91], v[104:107], v[176:179], v[88:91]
	v_mfma_f32_16x16x32_bf16 v[76:79], v[96:99], v[184:187], v[76:79]
	v_mfma_f32_16x16x32_bf16 v[72:75], v[104:107], v[184:187], v[72:75]
	v_mfma_f32_16x16x32_bf16 v[132:135], v[100:103], v[164:167], v[132:135]
	v_mfma_f32_16x16x32_bf16 v[128:131], v[108:111], v[164:167], v[128:131]
	v_mfma_f32_16x16x32_bf16 v[140:143], v[100:103], v[172:175], v[140:143]
	v_mfma_f32_16x16x32_bf16 v[136:139], v[108:111], v[172:175], v[136:139]
	v_mfma_f32_16x16x32_bf16 v[92:95], v[100:103], v[180:183], v[92:95]
	v_mfma_f32_16x16x32_bf16 v[88:91], v[108:111], v[180:183], v[88:91]
	v_mfma_f32_16x16x32_bf16 v[76:79], v[100:103], v[188:191], v[76:79]
	v_mfma_f32_16x16x32_bf16 v[72:75], v[108:111], v[188:191], v[72:75]
	s_setprio 0
	s_setprio 1
	v_mfma_f32_16x16x32_bf16 v[116:119], v[144:147], v[160:163], v[116:119]
	v_mfma_f32_16x16x32_bf16 v[112:115], v[152:155], v[160:163], v[112:115]
	v_mfma_f32_16x16x32_bf16 v[124:127], v[144:147], v[168:171], v[124:127]
	v_mfma_f32_16x16x32_bf16 v[120:123], v[152:155], v[168:171], v[120:123]
	v_mfma_f32_16x16x32_bf16 v[84:87], v[144:147], v[176:179], v[84:87]
	v_mfma_f32_16x16x32_bf16 v[80:83], v[152:155], v[176:179], v[80:83]
	v_mfma_f32_16x16x32_bf16 v[68:71], v[144:147], v[184:187], v[68:71]
	v_mfma_f32_16x16x32_bf16 v[64:67], v[152:155], v[184:187], v[64:67]
	v_mfma_f32_16x16x32_bf16 v[116:119], v[148:151], v[164:167], v[116:119]
	v_mfma_f32_16x16x32_bf16 v[112:115], v[156:159], v[164:167], v[112:115]
	v_mfma_f32_16x16x32_bf16 v[124:127], v[148:151], v[172:175], v[124:127]
	v_mfma_f32_16x16x32_bf16 v[120:123], v[156:159], v[172:175], v[120:123]
	v_mfma_f32_16x16x32_bf16 v[84:87], v[148:151], v[180:183], v[84:87]
	v_mfma_f32_16x16x32_bf16 v[80:83], v[156:159], v[180:183], v[80:83]
	v_mfma_f32_16x16x32_bf16 v[68:71], v[148:151], v[188:191], v[68:71]
	v_mfma_f32_16x16x32_bf16 v[64:67], v[156:159], v[188:191], v[64:67]
	s_setprio 0
	s_barrier
; #define PG8_BAR __builtin_amdgcn_s_barrier()
; template <class Epi, class Sched, bool ALIGN_EPI = false, bool SP2 = false>
; __device__ __forceinline__ void gemm_phase(PG8_LAS unsigned char* lds, const Gemm g, const Sched& S, const Epi& E, const int w0) {
;     ...
;             PG8_LDA(At, 1, 1); PG8_STAGE(PG8_SB(1, 0), b3, voffB); PG8_STAGE(PG8_SB(1, 1), b3 + hstep, voffB); PG8_STAGE(PG8_SA(1, 0), a3, voffA);
;             PG8_WAIT_V(8); PG8_WAIT_L(0); PG8_BAR; PG8_MMA(1, 0, At, B0); PG8_MMA(1, 1, At, B1); PG8_BAR; PG8_SCHED;
;             } else {
;             PG8_LDB(B0, 0, 0); PG8_SCHED; PG8_LDA(At, 0, 0); PG8_STAGE(PG8_SA(1, 1), a1 + hstep, voffA);
;             PG8_WAIT_L(8); PG8_BAR; PG8_WAIT_L(0); PG8_MMA(0, 0, At, B0); PG8_BAR; PG8_SCHED;
;             PG8_LDB(B1, 0, 1); PG8_STAGE(PG8_SB(0, 0), b2, voffB);
;             PG8_BAR; PG8_WAIT_L(0); PG8_MMA(0, 1, At, B1); PG8_BAR;
;             PG8_LDA(At, 0, 1); PG8_STAGE(PG8_SA(0, 0), a2, voffA);
;             PG8_BAR; PG8_WAIT_L(0); PG8_MMA(1, 0, At, B0); PG8_BAR; PG8_SCHED;
;             PG8_STAGE(PG8_SB(0, 1), b2 + hstep, voffB);
;             PG8_WAIT_V(6); PG8_BAR; PG8_MMA(1, 1, At, B1); PG8_BAR;
;             PG8_LDB(B0, 1, 0); PG8_SCHED; PG8_LDA(At, 1, 0); PG8_STAGE(PG8_SA(0, 1), a2 + hstep, voffA);
;             PG8_WAIT_L(8); PG8_BAR; PG8_WAIT_L(0); PG8_MMA(0, 0, At, B0); PG8_BAR; PG8_SCHED;
;             PG8_LDB(B1, 1, 1); PG8_STAGE(PG8_SB(1, 0), b3, voffB);
;             PG8_BAR; PG8_WAIT_L(0); PG8_MMA(0, 1, At, B1); PG8_BAR;
;             PG8_LDA(At, 1, 1); PG8_STAGE(PG8_SA(1, 0), a3, voffA);
;             PG8_BAR; PG8_WAIT_L(0); PG8_MMA(1, 0, At, B0); PG8_BAR; PG8_SCHED;
;             PG8_STAGE(PG8_SB(1, 1), b3 + hstep, voffB);
;             PG8_WAIT_V(6); PG8_BAR; PG8_MMA(1, 1, At, B1); PG8_BAR;
;             }
;         }
;         if constexpr (ALIGN_EPI) { if (wr == 0) PG8_BAR; }
;     __device__ __forceinline__ void operator()(const f32x4 (&acc)[2][2][4][2], const pg8::Unit& u, int wr, int wc, int fr_, int fq_) const {
;     ...
;         const int pn = u.pn; unsigned char* ws = ka_ws(); float* out = ka_out();
;         const float* ssp = (const float*)(ws + WS_SSP); const float* tab = (const float*)(ws + WS_TAB);
;         bf16_t *Q = (bf16_t*)(ws + WS_Q), *K = (bf16_t*)(ws + WS_K), *V = (bf16_t*)(ws + WS_V), *SGA = (bf16_t*)(ws + WS_SGA), *BGC = (bf16_t*)(ws + WS_BGC), *U = (bf16_t*)(ws + WS_U);
	s_add_i32 s12, s28, s55
	v_lshl_add_u64 v[210:211], v[210:211], 0, s[38:39]
	s_mov_b32 m0, s12
	ds_read_b128 v[160:163], v249 offset:49152
	ds_read_b128 v[164:167], v249 offset:50176
	ds_read_b128 v[168:171], v249 offset:51200
	ds_read_b128 v[172:175], v249 offset:52224
	ds_read_b128 v[176:179], v249 offset:53248
	ds_read_b128 v[180:183], v249 offset:54272
	ds_read_b128 v[184:187], v249 offset:55296
	ds_read_b128 v[188:191], v249 offset:56320
	global_load_lds_dwordx4 v[210:211], off
	s_add_i32 m0, s12, 0x2000
	s_add_u32 s10, s10, 0x40080
	v_lshl_add_u64 v[210:211], v[212:213], 0, s[38:39]
	s_addc_u32 s11, s11, 0
	s_add_i32 s12, s29, s55
	global_load_lds_dwordx4 v[210:211], off
	v_lshl_add_u64 v[210:211], s[10:11], 0, v[200:201]
	s_mov_b32 m0, s12
	s_nop 0
	global_load_lds_dwordx4 v[210:211], off
	v_lshl_add_u64 v[210:211], s[10:11], 0, v[204:205]
	s_add_i32 m0, s12, 0x2000
	s_nop 0
	global_load_lds_dwordx4 v[210:211], off
	v_lshl_add_u64 v[210:211], v[214:215], 0, s[38:39]
	s_mov_b32 m0, s91
	s_nop 0
	global_load_lds_dwordx4 v[210:211], off
	v_lshl_add_u64 v[210:211], v[216:217], 0, s[38:39]
	s_mov_b32 m0, s92
	s_nop 0
	global_load_lds_dwordx4 v[210:211], off
	s_waitcnt vmcnt(8)
	s_waitcnt lgkmcnt(0)
	s_barrier
	s_setprio 1
	s_waitcnt lgkmcnt(0)
	v_mfma_f32_16x16x32_bf16 v[60:63], v[96:99], v[160:163], v[60:63]
	v_mfma_f32_16x16x32_bf16 v[56:59], v[104:107], v[160:163], v[56:59]
	v_mfma_f32_16x16x32_bf16 v[44:47], v[96:99], v[168:171], v[44:47]
	v_mfma_f32_16x16x32_bf16 v[40:43], v[104:107], v[168:171], v[40:43]
	v_mfma_f32_16x16x32_bf16 v[28:31], v[96:99], v[176:179], v[28:31]
	v_mfma_f32_16x16x32_bf16 v[24:27], v[104:107], v[176:179], v[24:27]
	v_mfma_f32_16x16x32_bf16 v[12:15], v[96:99], v[184:187], v[12:15]
	v_mfma_f32_16x16x32_bf16 v[8:11], v[104:107], v[184:187], v[8:11]
	v_mfma_f32_16x16x32_bf16 v[60:63], v[100:103], v[164:167], v[60:63]
	v_mfma_f32_16x16x32_bf16 v[56:59], v[108:111], v[164:167], v[56:59]
	v_mfma_f32_16x16x32_bf16 v[44:47], v[100:103], v[172:175], v[44:47]
	v_mfma_f32_16x16x32_bf16 v[40:43], v[108:111], v[172:175], v[40:43]
	v_mfma_f32_16x16x32_bf16 v[28:31], v[100:103], v[180:183], v[28:31]
	v_mfma_f32_16x16x32_bf16 v[24:27], v[108:111], v[180:183], v[24:27]
	v_mfma_f32_16x16x32_bf16 v[12:15], v[100:103], v[188:191], v[12:15]
	v_mfma_f32_16x16x32_bf16 v[8:11], v[108:111], v[188:191], v[8:11]
	s_setprio 0
	s_setprio 1
	v_mfma_f32_16x16x32_bf16 v[52:55], v[144:147], v[160:163], v[52:55]
	v_mfma_f32_16x16x32_bf16 v[48:51], v[152:155], v[160:163], v[48:51]
	v_mfma_f32_16x16x32_bf16 v[36:39], v[144:147], v[168:171], v[36:39]
	v_mfma_f32_16x16x32_bf16 v[32:35], v[152:155], v[168:171], v[32:35]
	v_mfma_f32_16x16x32_bf16 v[20:23], v[144:147], v[176:179], v[20:23]
	v_mfma_f32_16x16x32_bf16 v[16:19], v[152:155], v[176:179], v[16:19]
	v_mfma_f32_16x16x32_bf16 v[4:7], v[144:147], v[184:187], v[4:7]
	v_mfma_f32_16x16x32_bf16 v[0:3], v[152:155], v[184:187], v[0:3]
	v_mfma_f32_16x16x32_bf16 v[52:55], v[148:151], v[164:167], v[52:55]
	v_mfma_f32_16x16x32_bf16 v[48:51], v[156:159], v[164:167], v[48:51]
	v_mfma_f32_16x16x32_bf16 v[36:39], v[148:151], v[172:175], v[36:39]
	v_mfma_f32_16x16x32_bf16 v[32:35], v[156:159], v[172:175], v[32:35]
	v_mfma_f32_16x16x32_bf16 v[20:23], v[148:151], v[180:183], v[20:23]
	v_mfma_f32_16x16x32_bf16 v[16:19], v[156:159], v[180:183], v[16:19]
	v_mfma_f32_16x16x32_bf16 v[4:7], v[148:151], v[188:191], v[4:7]
	v_mfma_f32_16x16x32_bf16 v[0:3], v[156:159], v[188:191], v[0:3]
	s_setprio 0
	s_barrier
	s_add_i32 s20, s20, 2
	s_add_u32 s8, s8, 0x100
	s_addc_u32 s9, s9, 0
	s_add_u32 s18, s18, 0x100
	s_addc_u32 s19, s19, 0
	s_cmp_gt_u32 s20, 13
	s_cbranch_scc0 .LBB0_277
	s_and_b64 vcc, exec, s[34:35]
	s_cbranch_vccz .LBB0_280
	s_barrier
.LBB0_280:
	s_branch .Lme_entry
.LBB0_580:
	s_andn2_b64 vcc, exec, s[14:15]
	s_mov_b64 s[4:5], -1
	s_cbranch_vccnz .LBB0_269
	s_andn2_b64 vcc, exec, s[26:27]
	s_cbranch_vccnz .LBB0_268
	s_barrier
	s_branch .LBB0_268
.Lme_entry:
	s_load_dwordx2 s[10:11], s[0:1], 0x80
	s_load_dwordx2 s[28:29], s[0:1], 0x78
	v_readlane_b32 s20, v255, 36
	s_lshl_b32 s71, s4, 8
	s_add_i32 s71, s71, s89
	v_and_or_b32 v210, v248, 15, s71
	v_lshrrev_b32_e32 v211, 4, v248
	v_lshlrev_b32_e32 v212, 6, v210
	v_lshl_add_u32 v212, v211, 4, v212
	v_add_u32_e32 v213, 0x2000, v212
	v_xor_b32_e32 v250, 16, v248
	v_lshlrev_b32_e32 v250, 2, v250
	v_xor_b32_e32 v251, 32, v248
	v_lshlrev_b32_e32 v251, 2, v251
	v_lshlrev_b32_e32 v214, 10, v210
	v_lshl_add_u32 v214, v211, 4, v214
	s_waitcnt lgkmcnt(0)
	global_load_dwordx4 v[144:147], v212, s[10:11]
	global_load_dwordx4 v[148:151], v212, s[10:11] offset:1024
	global_load_dwordx4 v[152:155], v212, s[10:11] offset:2048
	global_load_dwordx4 v[156:159], v212, s[10:11] offset:3072
	global_load_dwordx4 v[160:163], v213, s[10:11]
	global_load_dwordx4 v[164:167], v213, s[10:11] offset:1024
	global_load_dwordx4 v[168:171], v213, s[10:11] offset:2048
	global_load_dwordx4 v[172:175], v213, s[10:11] offset:3072
	s_cmp_gt_i32 s6, 2
	s_cbranch_scc1 .Lme_notq
	s_cmp_eq_u32 s6, 2
	s_cbranch_scc0 .Lme_isrope
	s_cmp_gt_u32 s93, 127
	s_cbranch_scc1 .Lme_ventry
.Lme_isrope:
	s_and_b32 s5, s4, 7
	s_lshl_b32 s5, s5, 8
	s_add_i32 s5, s5, s89
	v_and_b32_e32 v252, 15, v248
	v_add_u32_e32 v252, s5, v252
	s_mov_b32 s7, 0x1000
	s_mov_b32 s8, 0x5000
	s_cmp_gt_i32 s4, 63
	s_cbranch_scc0 .Lme_qprompt
	v_and_b32_e32 v252, 3, v248
	v_add_u32_e32 v252, 0x800, v252
	s_mov_b32 s7, 0
	s_mov_b32 s8, 0
.Lme_qprompt:
	v_lshlrev_b32_e32 v252, 8, v252
	v_lshl_add_u32 v252, v211, 5, v252
	s_add_u32 s12, s10, 0xfd00000
	s_addc_u32 s13, s11, 0
	global_load_dwordx4 v[96:99], v252, s[12:13]
	global_load_dwordx4 v[100:103], v252, s[12:13] offset:16
	global_load_dwordx4 v[104:107], v252, s[12:13] offset:128
	global_load_dwordx4 v[108:111], v252, s[12:13] offset:144
	v_add_u32_e32 v252, s7, v252
	global_load_dwordx4 v[218:221], v252, s[12:13]
	global_load_dwordx4 v[222:225], v252, s[12:13] offset:16
	global_load_dwordx4 v[226:229], v252, s[12:13] offset:128
	global_load_dwordx4 v[230:233], v252, s[12:13] offset:144
	v_add_u32_e32 v252, s7, v252
	s_lshl_b32 s9, s93, 1
	s_cmp_eq_u32 s6, 2
	s_cbranch_scc1 .Lme_kbase
	s_lshl_b32 s5, s6, 9
	s_add_i32 s5, s5, s9
	s_add_u32 s5, s5, 0xb200000
	s_branch .Lme_qkbase
.Lme_kbase:
	s_add_u32 s5, s9, 0xf400000
.Lme_qkbase:
	s_add_u32 s16, s10, s5
	s_addc_u32 s17, s11, 0
	s_mov_b32 s30, s48
	s_mov_b32 s31, s48
	v_lshlrev_b32_e32 v215, 8, v210
	v_lshl_add_u32 v215, v211, 4, v215
	s_waitcnt vmcnt(8)
	s_branch .Lme_reduce
.Lme_ventry:
	s_add_i32 s5, s93, 0xffffff80
	s_add_u32 s5, s5, 0xf820000
	s_add_u32 s16, s10, s5
	s_addc_u32 s17, s11, 0
	v_lshlrev_b32_e32 v215, 8, v210
	v_lshl_add_u32 v215, v211, 4, v215
	s_waitcnt vmcnt(0)
	s_branch .Lme_reduce

; __device__ __forceinline__ u32x4 pk8(f32x4 a, f32x4 b) { u32x4 w; w.x = pk2(a[0], a[1]); w.y = pk2(a[2], a[3]); w.z = pk2(b[0], b[1]); w.w = pk2(b[2], b[3]); return w; }
;     __device__ __forceinline__ void operator()(const f32x4 (&acc)[2][2][4][2], const pg8::Unit& u, int wr, int wc, int fr_, int fq_) const {
;     ...
;                 const int k = it - 2, ai = k >> 2, m = k & 3, row = row0 + ai * 128 + m * 16;
;                 float sq = (ld[k].ss[0] + ld[k].ss[1]) + (ld[k].ss[2] + ld[k].ss[3]); sq += __shfl_xor(sq, 16); sq += __shfl_xor(sq, 32);
;                 const float rs = __builtin_amdgcn_rsqf(sq * (1.f / 1024.f) + EPS);
;                 const f32x4 a0 = acc[ai][0][m][0] * rs, a1 = acc[ai][0][m][1] * rs, b0 = acc[ai][1][m][0] * rs, b1 = acc[ai][1][m][1] * rs;
;                 if (rope) {
;                     const f32x4 c0 = ld[k].c0, c1 = ld[k].c1, s0 = ld[k].s0, s1 = ld[k].s1;
;                     f32x4 o1a = a0 * c0 - b0 * s0, o1b = a1 * c1 - b1 * s1, o2a = b0 * c0 + a0 * s0, o2b = b1 * c1 + a1 * s1;
;                     if (pn < 2) {
;                         o1a *= QS; o1b *= QS; o2a *= QS; o2b *= QS;
;                         bf16_t* q = Q + (size_t)row * 512 + (4 * pn + wc) * 64 + fq * 8;
;                         gst<u32x4>(q, pk8(o1a, o1b)); gst<u32x4>(q + 32, pk8(o2a, o2b));
.Lme_reduce:
	v_add_f32_e32 v144, v144, v145
	v_add_f32_e32 v146, v146, v147
	v_add_f32_e32 v148, v148, v149
	v_add_f32_e32 v150, v150, v151
	v_add_f32_e32 v152, v152, v153
	v_add_f32_e32 v154, v154, v155
	v_add_f32_e32 v156, v156, v157
	v_add_f32_e32 v158, v158, v159
	v_add_f32_e32 v160, v160, v161
	v_add_f32_e32 v162, v162, v163
	v_add_f32_e32 v164, v164, v165
	v_add_f32_e32 v166, v166, v167
	v_add_f32_e32 v168, v168, v169
	v_add_f32_e32 v170, v170, v171
	v_add_f32_e32 v172, v172, v173
	v_add_f32_e32 v174, v174, v175
	v_add_f32_e32 v144, v144, v146
	v_add_f32_e32 v148, v148, v150
	v_add_f32_e32 v152, v152, v154
	v_add_f32_e32 v156, v156, v158
	v_add_f32_e32 v160, v160, v162
	v_add_f32_e32 v164, v164, v166
	v_add_f32_e32 v168, v168, v170
	v_add_f32_e32 v172, v172, v174
	ds_bpermute_b32 v145, v250, v144
	ds_bpermute_b32 v149, v250, v148
	ds_bpermute_b32 v153, v250, v152
	ds_bpermute_b32 v157, v250, v156
	ds_bpermute_b32 v161, v250, v160
	ds_bpermute_b32 v165, v250, v164
	ds_bpermute_b32 v169, v250, v168
	ds_bpermute_b32 v173, v250, v172
	s_waitcnt lgkmcnt(0)
	v_add_f32_e32 v144, v144, v145
	v_add_f32_e32 v148, v148, v149
	v_add_f32_e32 v152, v152, v153
	v_add_f32_e32 v156, v156, v157
	v_add_f32_e32 v160, v160, v161
	v_add_f32_e32 v164, v164, v165
	v_add_f32_e32 v168, v168, v169
	v_add_f32_e32 v172, v172, v173
	ds_bpermute_b32 v145, v251, v144
	ds_bpermute_b32 v149, v251, v148
	ds_bpermute_b32 v153, v251, v152
	ds_bpermute_b32 v157, v251, v156
	ds_bpermute_b32 v161, v251, v160
	ds_bpermute_b32 v165, v251, v164
	ds_bpermute_b32 v169, v251, v168
	ds_bpermute_b32 v173, v251, v172
	s_waitcnt lgkmcnt(0)
	v_add_f32_e32 v144, v144, v145
	v_add_f32_e32 v148, v148, v149
	v_add_f32_e32 v152, v152, v153
	v_add_f32_e32 v156, v156, v157
	v_add_f32_e32 v160, v160, v161
	v_add_f32_e32 v164, v164, v165
	v_add_f32_e32 v168, v168, v169
	v_add_f32_e32 v172, v172, v173
	v_fmamk_f32 v144, v144, 0x3a800000, v243
	v_fmamk_f32 v148, v148, 0x3a800000, v243
	v_fmamk_f32 v152, v152, 0x3a800000, v243
	v_fmamk_f32 v156, v156, 0x3a800000, v243
	v_fmamk_f32 v160, v160, 0x3a800000, v243
	v_fmamk_f32 v164, v164, 0x3a800000, v243
	v_fmamk_f32 v168, v168, 0x3a800000, v243
	v_fmamk_f32 v172, v172, 0x3a800000, v243
	v_rsq_f32_e32 v176, v144
	v_rsq_f32_e32 v178, v148
	v_rsq_f32_e32 v180, v152
	v_rsq_f32_e32 v182, v156
	v_rsq_f32_e32 v184, v160
	v_rsq_f32_e32 v186, v164
	v_rsq_f32_e32 v188, v168
	v_rsq_f32_e32 v190, v172
	s_cmp_gt_i32 s6, 8
	s_cbranch_scc1 .Lme_upath
	s_cmp_gt_i32 s6, 4
	s_cbranch_scc1 .Lme_bpath
	s_cmp_gt_i32 s6, 2
	s_cbranch_scc1 .Lme_spath
	s_cmp_eq_u32 s6, 2
	s_cbranch_scc1 .Lme_kvpath
	global_load_dwordx4 v[144:147], v252, s[12:13]
	global_load_dwordx4 v[148:151], v252, s[12:13] offset:16
	global_load_dwordx4 v[152:155], v252, s[12:13] offset:128
	global_load_dwordx4 v[156:159], v252, s[12:13] offset:144
	v_add_u32_e32 v252, s7, v252
	global_load_dwordx4 v[160:163], v252, s[12:13]
	global_load_dwordx4 v[164:167], v252, s[12:13] offset:16
	global_load_dwordx4 v[168:171], v252, s[12:13] offset:128
	global_load_dwordx4 v[172:175], v252, s[12:13] offset:144
	v_add_u32_e32 v252, s8, v252
	v_pk_mul_f32 v[132:133], v[132:133], v[176:177] op_sel_hi:[1,0]
	v_pk_mul_f32 v[134:135], v[134:135], v[176:177] op_sel_hi:[1,0]
	v_pk_mul_f32 v[128:129], v[128:129], v[176:177] op_sel_hi:[1,0]
	v_pk_mul_f32 v[130:131], v[130:131], v[176:177] op_sel_hi:[1,0]
	v_pk_mul_f32 v[116:117], v[116:117], v[176:177] op_sel_hi:[1,0]
	v_pk_mul_f32 v[118:119], v[118:119], v[176:177] op_sel_hi:[1,0]
	v_pk_mul_f32 v[112:113], v[112:113], v[176:177] op_sel_hi:[1,0]
	v_pk_mul_f32 v[114:115], v[114:115], v[176:177] op_sel_hi:[1,0]
	s_waitcnt vmcnt(12)
	v_pk_mul_f32 v[234:235], v[116:117], v[104:105]
	v_pk_mul_f32 v[236:237], v[118:119], v[106:107]
	v_pk_mul_f32 v[238:239], v[112:113], v[108:109]
	v_pk_mul_f32 v[240:241], v[114:115], v[110:111]
	v_pk_fma_f32 v[234:235], v[132:133], v[96:97], v[234:235] neg_lo:[0,0,1] neg_hi:[0,0,1]
	v_pk_fma_f32 v[236:237], v[134:135], v[98:99], v[236:237] neg_lo:[0,0,1] neg_hi:[0,0,1]
	v_pk_fma_f32 v[238:239], v[128:129], v[100:101], v[238:239] neg_lo:[0,0,1] neg_hi:[0,0,1]
	v_pk_fma_f32 v[240:241], v[130:131], v[102:103], v[240:241] neg_lo:[0,0,1] neg_hi:[0,0,1]
	v_pk_mul_f32 v[104:105], v[132:133], v[104:105]
	v_pk_mul_f32 v[106:107], v[134:135], v[106:107]
	v_pk_mul_f32 v[108:109], v[128:129], v[108:109]
	v_pk_mul_f32 v[110:111], v[130:131], v[110:111]
	v_pk_fma_f32 v[104:105], v[116:117], v[96:97], v[104:105]
	v_pk_fma_f32 v[106:107], v[118:119], v[98:99], v[106:107]
	v_pk_fma_f32 v[108:109], v[112:113], v[100:101], v[108:109]
	v_pk_fma_f32 v[110:111], v[114:115], v[102:103], v[110:111]
	v_pk_mul_f32 v[234:235], v[234:235], s[30:31]
	v_pk_mul_f32 v[236:237], v[236:237], s[30:31]
	v_pk_mul_f32 v[238:239], v[238:239], s[30:31]
	v_pk_mul_f32 v[240:241], v[240:241], s[30:31]
	v_pk_mul_f32 v[104:105], v[104:105], s[30:31]
	v_pk_mul_f32 v[106:107], v[106:107], s[30:31]
	v_pk_mul_f32 v[108:109], v[108:109], s[30:31]
	v_pk_mul_f32 v[110:111], v[110:111], s[30:31]
	v_cvt_pk_bf16_f32 v132, v234, v235
	v_cvt_pk_bf16_f32 v133, v236, v237
	v_cvt_pk_bf16_f32 v134, v238, v239
	v_cvt_pk_bf16_f32 v135, v240, v241
	global_store_dwordx4 v214, v[132:135], s[16:17]
	v_cvt_pk_bf16_f32 v116, v104, v105
	v_cvt_pk_bf16_f32 v117, v106, v107
	v_cvt_pk_bf16_f32 v118, v108, v109
	v_cvt_pk_bf16_f32 v119, v110, v111
	global_store_dwordx4 v214, v[116:119], s[16:17] offset:64
	s_add_u32 s16, s16, 0x4000
	s_addc_u32 s17, s17, 0
	global_load_dwordx4 v[96:99], v252, s[12:13]
	global_load_dwordx4 v[100:103], v252, s[12:13] offset:16
	global_load_dwordx4 v[104:107], v252, s[12:13] offset:128
	global_load_dwordx4 v[108:111], v252, s[12:13] offset:144
	v_add_u32_e32 v252, s7, v252
	v_pk_mul_f32 v[140:141], v[140:141], v[178:179] op_sel_hi:[1,0]
	v_pk_mul_f32 v[142:143], v[142:143], v[178:179] op_sel_hi:[1,0]
	v_pk_mul_f32 v[136:137], v[136:137], v[178:179] op_sel_hi:[1,0]
	v_pk_mul_f32 v[138:139], v[138:139], v[178:179] op_sel_hi:[1,0]
	v_pk_mul_f32 v[124:125], v[124:125], v[178:179] op_sel_hi:[1,0]
	v_pk_mul_f32 v[126:127], v[126:127], v[178:179] op_sel_hi:[1,0]
	v_pk_mul_f32 v[120:121], v[120:121], v[178:179] op_sel_hi:[1,0]
	v_pk_mul_f32 v[122:123], v[122:123], v[178:179] op_sel_hi:[1,0]
	s_waitcnt vmcnt(14)
; __device__ __forceinline__ u32x4 pk8(f32x4 a, f32x4 b) { u32x4 w; w.x = pk2(a[0], a[1]); w.y = pk2(a[2], a[3]); w.z = pk2(b[0], b[1]); w.w = pk2(b[2], b[3]); return w; }
;     __device__ __forceinline__ void operator()(const f32x4 (&acc)[2][2][4][2], const pg8::Unit& u, int wr, int wc, int fr_, int fq_) const {
;     ...
;                 const f32x4 a0 = acc[ai][0][m][0] * rs, a1 = acc[ai][0][m][1] * rs, b0 = acc[ai][1][m][0] * rs, b1 = acc[ai][1][m][1] * rs;
;                 if (rope) {
;                     const f32x4 c0 = ld[k].c0, c1 = ld[k].c1, s0 = ld[k].s0, s1 = ld[k].s1;
;                     f32x4 o1a = a0 * c0 - b0 * s0, o1b = a1 * c1 - b1 * s1, o2a = b0 * c0 + a0 * s0, o2b = b1 * c1 + a1 * s1;
;                     if (pn < 2) {
;                         o1a *= QS; o1b *= QS; o2a *= QS; o2b *= QS;
;                         bf16_t* q = Q + (size_t)row * 512 + (4 * pn + wc) * 64 + fq * 8;
;                         gst<u32x4>(q, pk8(o1a, o1b)); gst<u32x4>(q + 32, pk8(o2a, o2b));
	v_pk_mul_f32 v[234:235], v[124:125], v[226:227]
	v_pk_mul_f32 v[236:237], v[126:127], v[228:229]
	v_pk_mul_f32 v[238:239], v[120:121], v[230:231]
	v_pk_mul_f32 v[240:241], v[122:123], v[232:233]
	v_pk_fma_f32 v[234:235], v[140:141], v[218:219], v[234:235] neg_lo:[0,0,1] neg_hi:[0,0,1]
	v_pk_fma_f32 v[236:237], v[142:143], v[220:221], v[236:237] neg_lo:[0,0,1] neg_hi:[0,0,1]
	v_pk_fma_f32 v[238:239], v[136:137], v[222:223], v[238:239] neg_lo:[0,0,1] neg_hi:[0,0,1]
	v_pk_fma_f32 v[240:241], v[138:139], v[224:225], v[240:241] neg_lo:[0,0,1] neg_hi:[0,0,1]
	v_pk_mul_f32 v[226:227], v[140:141], v[226:227]
	v_pk_mul_f32 v[228:229], v[142:143], v[228:229]
	v_pk_mul_f32 v[230:231], v[136:137], v[230:231]
	v_pk_mul_f32 v[232:233], v[138:139], v[232:233]
	v_pk_fma_f32 v[226:227], v[124:125], v[218:219], v[226:227]
	v_pk_fma_f32 v[228:229], v[126:127], v[220:221], v[228:229]
	v_pk_fma_f32 v[230:231], v[120:121], v[222:223], v[230:231]
	v_pk_fma_f32 v[232:233], v[122:123], v[224:225], v[232:233]
	v_pk_mul_f32 v[234:235], v[234:235], s[30:31]
	v_pk_mul_f32 v[236:237], v[236:237], s[30:31]
	v_pk_mul_f32 v[238:239], v[238:239], s[30:31]
	v_pk_mul_f32 v[240:241], v[240:241], s[30:31]
	v_pk_mul_f32 v[226:227], v[226:227], s[30:31]
	v_pk_mul_f32 v[228:229], v[228:229], s[30:31]
	v_pk_mul_f32 v[230:231], v[230:231], s[30:31]
	v_pk_mul_f32 v[232:233], v[232:233], s[30:31]
	v_cvt_pk_bf16_f32 v140, v234, v235
	v_cvt_pk_bf16_f32 v141, v236, v237
	v_cvt_pk_bf16_f32 v142, v238, v239
	v_cvt_pk_bf16_f32 v143, v240, v241
	global_store_dwordx4 v214, v[140:143], s[16:17]
	v_cvt_pk_bf16_f32 v124, v226, v227
	v_cvt_pk_bf16_f32 v125, v228, v229
	v_cvt_pk_bf16_f32 v126, v230, v231
	v_cvt_pk_bf16_f32 v127, v232, v233
	global_store_dwordx4 v214, v[124:127], s[16:17] offset:64
	s_add_u32 s16, s16, 0x4000
	s_addc_u32 s17, s17, 0
	global_load_dwordx4 v[218:221], v252, s[12:13]
	global_load_dwordx4 v[222:225], v252, s[12:13] offset:16
	global_load_dwordx4 v[226:229], v252, s[12:13] offset:128
	global_load_dwordx4 v[230:233], v252, s[12:13] offset:144
	v_add_u32_e32 v252, s7, v252
	v_pk_mul_f32 v[92:93], v[92:93], v[180:181] op_sel_hi:[1,0]
	v_pk_mul_f32 v[94:95], v[94:95], v[180:181] op_sel_hi:[1,0]
	v_pk_mul_f32 v[88:89], v[88:89], v[180:181] op_sel_hi:[1,0]
	v_pk_mul_f32 v[90:91], v[90:91], v[180:181] op_sel_hi:[1,0]
	v_pk_mul_f32 v[84:85], v[84:85], v[180:181] op_sel_hi:[1,0]
	v_pk_mul_f32 v[86:87], v[86:87], v[180:181] op_sel_hi:[1,0]
	v_pk_mul_f32 v[80:81], v[80:81], v[180:181] op_sel_hi:[1,0]
	v_pk_mul_f32 v[82:83], v[82:83], v[180:181] op_sel_hi:[1,0]
	s_waitcnt vmcnt(16)
	v_pk_mul_f32 v[234:235], v[84:85], v[152:153]
	v_pk_mul_f32 v[236:237], v[86:87], v[154:155]
	v_pk_mul_f32 v[238:239], v[80:81], v[156:157]
	v_pk_mul_f32 v[240:241], v[82:83], v[158:159]
	v_pk_fma_f32 v[234:235], v[92:93], v[144:145], v[234:235] neg_lo:[0,0,1] neg_hi:[0,0,1]
	v_pk_fma_f32 v[236:237], v[94:95], v[146:147], v[236:237] neg_lo:[0,0,1] neg_hi:[0,0,1]
	v_pk_fma_f32 v[238:239], v[88:89], v[148:149], v[238:239] neg_lo:[0,0,1] neg_hi:[0,0,1]
	v_pk_fma_f32 v[240:241], v[90:91], v[150:151], v[240:241] neg_lo:[0,0,1] neg_hi:[0,0,1]
	v_pk_mul_f32 v[152:153], v[92:93], v[152:153]
	v_pk_mul_f32 v[154:155], v[94:95], v[154:155]
	v_pk_mul_f32 v[156:157], v[88:89], v[156:157]
	v_pk_mul_f32 v[158:159], v[90:91], v[158:159]
	v_pk_fma_f32 v[152:153], v[84:85], v[144:145], v[152:153]
	v_pk_fma_f32 v[154:155], v[86:87], v[146:147], v[154:155]
	v_pk_fma_f32 v[156:157], v[80:81], v[148:149], v[156:157]
	v_pk_fma_f32 v[158:159], v[82:83], v[150:151], v[158:159]
	v_pk_mul_f32 v[234:235], v[234:235], s[30:31]
	v_pk_mul_f32 v[236:237], v[236:237], s[30:31]
	v_pk_mul_f32 v[238:239], v[238:239], s[30:31]
	v_pk_mul_f32 v[240:241], v[240:241], s[30:31]
	v_pk_mul_f32 v[152:153], v[152:153], s[30:31]
	v_pk_mul_f32 v[154:155], v[154:155], s[30:31]
	v_pk_mul_f32 v[156:157], v[156:157], s[30:31]
	v_pk_mul_f32 v[158:159], v[158:159], s[30:31]
	v_cvt_pk_bf16_f32 v92, v234, v235
	v_cvt_pk_bf16_f32 v93, v236, v237
	v_cvt_pk_bf16_f32 v94, v238, v239
	v_cvt_pk_bf16_f32 v95, v240, v241
	global_store_dwordx4 v214, v[92:95], s[16:17]
	v_cvt_pk_bf16_f32 v84, v152, v153
	v_cvt_pk_bf16_f32 v85, v154, v155
	v_cvt_pk_bf16_f32 v86, v156, v157
	v_cvt_pk_bf16_f32 v87, v158, v159
	global_store_dwordx4 v214, v[84:87], s[16:17] offset:64
	s_add_u32 s16, s16, 0x4000
	s_addc_u32 s17, s17, 0
	global_load_dwordx4 v[144:147], v252, s[12:13]
	global_load_dwordx4 v[148:151], v252, s[12:13] offset:16
	global_load_dwordx4 v[152:155], v252, s[12:13] offset:128
	global_load_dwordx4 v[156:159], v252, s[12:13] offset:144
	v_add_u32_e32 v252, s7, v252
	v_pk_mul_f32 v[76:77], v[76:77], v[182:183] op_sel_hi:[1,0]
	v_pk_mul_f32 v[78:79], v[78:79], v[182:183] op_sel_hi:[1,0]
	v_pk_mul_f32 v[72:73], v[72:73], v[182:183] op_sel_hi:[1,0]
	v_pk_mul_f32 v[74:75], v[74:75], v[182:183] op_sel_hi:[1,0]
	v_pk_mul_f32 v[68:69], v[68:69], v[182:183] op_sel_hi:[1,0]
	v_pk_mul_f32 v[70:71], v[70:71], v[182:183] op_sel_hi:[1,0]
	v_pk_mul_f32 v[64:65], v[64:65], v[182:183] op_sel_hi:[1,0]
	v_pk_mul_f32 v[66:67], v[66:67], v[182:183] op_sel_hi:[1,0]
	s_waitcnt vmcnt(18)
; __device__ __forceinline__ u32x4 pk8(f32x4 a, f32x4 b) { u32x4 w; w.x = pk2(a[0], a[1]); w.y = pk2(a[2], a[3]); w.z = pk2(b[0], b[1]); w.w = pk2(b[2], b[3]); return w; }
;     __device__ __forceinline__ void operator()(const f32x4 (&acc)[2][2][4][2], const pg8::Unit& u, int wr, int wc, int fr_, int fq_) const {
;     ...
;                 const f32x4 a0 = acc[ai][0][m][0] * rs, a1 = acc[ai][0][m][1] * rs, b0 = acc[ai][1][m][0] * rs, b1 = acc[ai][1][m][1] * rs;
;                 if (rope) {
;                     const f32x4 c0 = ld[k].c0, c1 = ld[k].c1, s0 = ld[k].s0, s1 = ld[k].s1;
;                     f32x4 o1a = a0 * c0 - b0 * s0, o1b = a1 * c1 - b1 * s1, o2a = b0 * c0 + a0 * s0, o2b = b1 * c1 + a1 * s1;
;                     if (pn < 2) {
;                         o1a *= QS; o1b *= QS; o2a *= QS; o2b *= QS;
;                         bf16_t* q = Q + (size_t)row * 512 + (4 * pn + wc) * 64 + fq * 8;
;                         gst<u32x4>(q, pk8(o1a, o1b)); gst<u32x4>(q + 32, pk8(o2a, o2b));
	v_pk_mul_f32 v[234:235], v[68:69], v[168:169]
	v_pk_mul_f32 v[236:237], v[70:71], v[170:171]
	v_pk_mul_f32 v[238:239], v[64:65], v[172:173]
	v_pk_mul_f32 v[240:241], v[66:67], v[174:175]
	v_pk_fma_f32 v[234:235], v[76:77], v[160:161], v[234:235] neg_lo:[0,0,1] neg_hi:[0,0,1]
	v_pk_fma_f32 v[236:237], v[78:79], v[162:163], v[236:237] neg_lo:[0,0,1] neg_hi:[0,0,1]
	v_pk_fma_f32 v[238:239], v[72:73], v[164:165], v[238:239] neg_lo:[0,0,1] neg_hi:[0,0,1]
	v_pk_fma_f32 v[240:241], v[74:75], v[166:167], v[240:241] neg_lo:[0,0,1] neg_hi:[0,0,1]
	v_pk_mul_f32 v[168:169], v[76:77], v[168:169]
	v_pk_mul_f32 v[170:171], v[78:79], v[170:171]
	v_pk_mul_f32 v[172:173], v[72:73], v[172:173]
	v_pk_mul_f32 v[174:175], v[74:75], v[174:175]
	v_pk_fma_f32 v[168:169], v[68:69], v[160:161], v[168:169]
	v_pk_fma_f32 v[170:171], v[70:71], v[162:163], v[170:171]
	v_pk_fma_f32 v[172:173], v[64:65], v[164:165], v[172:173]
	v_pk_fma_f32 v[174:175], v[66:67], v[166:167], v[174:175]
	v_pk_mul_f32 v[234:235], v[234:235], s[30:31]
	v_pk_mul_f32 v[236:237], v[236:237], s[30:31]
	v_pk_mul_f32 v[238:239], v[238:239], s[30:31]
	v_pk_mul_f32 v[240:241], v[240:241], s[30:31]
	v_pk_mul_f32 v[168:169], v[168:169], s[30:31]
	v_pk_mul_f32 v[170:171], v[170:171], s[30:31]
	v_pk_mul_f32 v[172:173], v[172:173], s[30:31]
	v_pk_mul_f32 v[174:175], v[174:175], s[30:31]
	v_cvt_pk_bf16_f32 v76, v234, v235
	v_cvt_pk_bf16_f32 v77, v236, v237
	v_cvt_pk_bf16_f32 v78, v238, v239
	v_cvt_pk_bf16_f32 v79, v240, v241
	global_store_dwordx4 v214, v[76:79], s[16:17]
	v_cvt_pk_bf16_f32 v68, v168, v169
	v_cvt_pk_bf16_f32 v69, v170, v171
	v_cvt_pk_bf16_f32 v70, v172, v173
	v_cvt_pk_bf16_f32 v71, v174, v175
	global_store_dwordx4 v214, v[68:71], s[16:17] offset:64
	s_add_u32 s16, s16, 0x14000
	s_addc_u32 s17, s17, 0
	global_load_dwordx4 v[160:163], v252, s[12:13]
	global_load_dwordx4 v[164:167], v252, s[12:13] offset:16
	global_load_dwordx4 v[168:171], v252, s[12:13] offset:128
	global_load_dwordx4 v[172:175], v252, s[12:13] offset:144
	v_pk_mul_f32 v[60:61], v[60:61], v[184:185] op_sel_hi:[1,0]
	v_pk_mul_f32 v[62:63], v[62:63], v[184:185] op_sel_hi:[1,0]
	v_pk_mul_f32 v[56:57], v[56:57], v[184:185] op_sel_hi:[1,0]
	v_pk_mul_f32 v[58:59], v[58:59], v[184:185] op_sel_hi:[1,0]
	v_pk_mul_f32 v[52:53], v[52:53], v[184:185] op_sel_hi:[1,0]
	v_pk_mul_f32 v[54:55], v[54:55], v[184:185] op_sel_hi:[1,0]
	v_pk_mul_f32 v[48:49], v[48:49], v[184:185] op_sel_hi:[1,0]
	v_pk_mul_f32 v[50:51], v[50:51], v[184:185] op_sel_hi:[1,0]
	s_waitcnt vmcnt(18)
	v_pk_mul_f32 v[234:235], v[52:53], v[104:105]
	v_pk_mul_f32 v[236:237], v[54:55], v[106:107]
	v_pk_mul_f32 v[238:239], v[48:49], v[108:109]
	v_pk_mul_f32 v[240:241], v[50:51], v[110:111]
	v_pk_fma_f32 v[234:235], v[60:61], v[96:97], v[234:235] neg_lo:[0,0,1] neg_hi:[0,0,1]
	v_pk_fma_f32 v[236:237], v[62:63], v[98:99], v[236:237] neg_lo:[0,0,1] neg_hi:[0,0,1]
	v_pk_fma_f32 v[238:239], v[56:57], v[100:101], v[238:239] neg_lo:[0,0,1] neg_hi:[0,0,1]
	v_pk_fma_f32 v[240:241], v[58:59], v[102:103], v[240:241] neg_lo:[0,0,1] neg_hi:[0,0,1]
	v_pk_mul_f32 v[104:105], v[60:61], v[104:105]
	v_pk_mul_f32 v[106:107], v[62:63], v[106:107]
	v_pk_mul_f32 v[108:109], v[56:57], v[108:109]
	v_pk_mul_f32 v[110:111], v[58:59], v[110:111]
	v_pk_fma_f32 v[104:105], v[52:53], v[96:97], v[104:105]
	v_pk_fma_f32 v[106:107], v[54:55], v[98:99], v[106:107]
	v_pk_fma_f32 v[108:109], v[48:49], v[100:101], v[108:109]
	v_pk_fma_f32 v[110:111], v[50:51], v[102:103], v[110:111]
	v_pk_mul_f32 v[234:235], v[234:235], s[30:31]
	v_pk_mul_f32 v[236:237], v[236:237], s[30:31]
	v_pk_mul_f32 v[238:239], v[238:239], s[30:31]
	v_pk_mul_f32 v[240:241], v[240:241], s[30:31]
	v_pk_mul_f32 v[104:105], v[104:105], s[30:31]
	v_pk_mul_f32 v[106:107], v[106:107], s[30:31]
	v_pk_mul_f32 v[108:109], v[108:109], s[30:31]
	v_pk_mul_f32 v[110:111], v[110:111], s[30:31]
	v_cvt_pk_bf16_f32 v60, v234, v235
	v_cvt_pk_bf16_f32 v61, v236, v237
	v_cvt_pk_bf16_f32 v62, v238, v239
	v_cvt_pk_bf16_f32 v63, v240, v241
	global_store_dwordx4 v214, v[60:63], s[16:17]
	v_cvt_pk_bf16_f32 v52, v104, v105
	v_cvt_pk_bf16_f32 v53, v106, v107
	v_cvt_pk_bf16_f32 v54, v108, v109
	v_cvt_pk_bf16_f32 v55, v110, v111
	global_store_dwordx4 v214, v[52:55], s[16:17] offset:64
	s_add_u32 s16, s16, 0x4000
	s_addc_u32 s17, s17, 0
	v_pk_mul_f32 v[44:45], v[44:45], v[186:187] op_sel_hi:[1,0]
	v_pk_mul_f32 v[46:47], v[46:47], v[186:187] op_sel_hi:[1,0]
	v_pk_mul_f32 v[40:41], v[40:41], v[186:187] op_sel_hi:[1,0]
	v_pk_mul_f32 v[42:43], v[42:43], v[186:187] op_sel_hi:[1,0]
	v_pk_mul_f32 v[36:37], v[36:37], v[186:187] op_sel_hi:[1,0]
	v_pk_mul_f32 v[38:39], v[38:39], v[186:187] op_sel_hi:[1,0]
	v_pk_mul_f32 v[32:33], v[32:33], v[186:187] op_sel_hi:[1,0]
	v_pk_mul_f32 v[34:35], v[34:35], v[186:187] op_sel_hi:[1,0]
	s_waitcnt vmcnt(14)
; __device__ __forceinline__ u32x4 pk8(f32x4 a, f32x4 b) { u32x4 w; w.x = pk2(a[0], a[1]); w.y = pk2(a[2], a[3]); w.z = pk2(b[0], b[1]); w.w = pk2(b[2], b[3]); return w; }
;     __device__ __forceinline__ void operator()(const f32x4 (&acc)[2][2][4][2], const pg8::Unit& u, int wr, int wc, int fr_, int fq_) const {
;     ...
;                 const f32x4 a0 = acc[ai][0][m][0] * rs, a1 = acc[ai][0][m][1] * rs, b0 = acc[ai][1][m][0] * rs, b1 = acc[ai][1][m][1] * rs;
;                 if (rope) {
;                     const f32x4 c0 = ld[k].c0, c1 = ld[k].c1, s0 = ld[k].s0, s1 = ld[k].s1;
;                     f32x4 o1a = a0 * c0 - b0 * s0, o1b = a1 * c1 - b1 * s1, o2a = b0 * c0 + a0 * s0, o2b = b1 * c1 + a1 * s1;
;                     if (pn < 2) {
;                         o1a *= QS; o1b *= QS; o2a *= QS; o2b *= QS;
;                         bf16_t* q = Q + (size_t)row * 512 + (4 * pn + wc) * 64 + fq * 8;
;                         gst<u32x4>(q, pk8(o1a, o1b)); gst<u32x4>(q + 32, pk8(o2a, o2b));
	v_pk_mul_f32 v[234:235], v[36:37], v[226:227]
	v_pk_mul_f32 v[236:237], v[38:39], v[228:229]
	v_pk_mul_f32 v[238:239], v[32:33], v[230:231]
	v_pk_mul_f32 v[240:241], v[34:35], v[232:233]
	v_pk_fma_f32 v[234:235], v[44:45], v[218:219], v[234:235] neg_lo:[0,0,1] neg_hi:[0,0,1]
	v_pk_fma_f32 v[236:237], v[46:47], v[220:221], v[236:237] neg_lo:[0,0,1] neg_hi:[0,0,1]
	v_pk_fma_f32 v[238:239], v[40:41], v[222:223], v[238:239] neg_lo:[0,0,1] neg_hi:[0,0,1]
	v_pk_fma_f32 v[240:241], v[42:43], v[224:225], v[240:241] neg_lo:[0,0,1] neg_hi:[0,0,1]
	v_pk_mul_f32 v[226:227], v[44:45], v[226:227]
	v_pk_mul_f32 v[228:229], v[46:47], v[228:229]
	v_pk_mul_f32 v[230:231], v[40:41], v[230:231]
	v_pk_mul_f32 v[232:233], v[42:43], v[232:233]
	v_pk_fma_f32 v[226:227], v[36:37], v[218:219], v[226:227]
	v_pk_fma_f32 v[228:229], v[38:39], v[220:221], v[228:229]
	v_pk_fma_f32 v[230:231], v[32:33], v[222:223], v[230:231]
	v_pk_fma_f32 v[232:233], v[34:35], v[224:225], v[232:233]
	v_pk_mul_f32 v[234:235], v[234:235], s[30:31]
	v_pk_mul_f32 v[236:237], v[236:237], s[30:31]
	v_pk_mul_f32 v[238:239], v[238:239], s[30:31]
	v_pk_mul_f32 v[240:241], v[240:241], s[30:31]
	v_pk_mul_f32 v[226:227], v[226:227], s[30:31]
	v_pk_mul_f32 v[228:229], v[228:229], s[30:31]
	v_pk_mul_f32 v[230:231], v[230:231], s[30:31]
	v_pk_mul_f32 v[232:233], v[232:233], s[30:31]
	v_cvt_pk_bf16_f32 v44, v234, v235
	v_cvt_pk_bf16_f32 v45, v236, v237
	v_cvt_pk_bf16_f32 v46, v238, v239
	v_cvt_pk_bf16_f32 v47, v240, v241
	global_store_dwordx4 v214, v[44:47], s[16:17]
	v_cvt_pk_bf16_f32 v36, v226, v227
	v_cvt_pk_bf16_f32 v37, v228, v229
	v_cvt_pk_bf16_f32 v38, v230, v231
	v_cvt_pk_bf16_f32 v39, v232, v233
	global_store_dwordx4 v214, v[36:39], s[16:17] offset:64
	s_add_u32 s16, s16, 0x4000
	s_addc_u32 s17, s17, 0
	v_pk_mul_f32 v[28:29], v[28:29], v[188:189] op_sel_hi:[1,0]
	v_pk_mul_f32 v[30:31], v[30:31], v[188:189] op_sel_hi:[1,0]
	v_pk_mul_f32 v[24:25], v[24:25], v[188:189] op_sel_hi:[1,0]
	v_pk_mul_f32 v[26:27], v[26:27], v[188:189] op_sel_hi:[1,0]
	v_pk_mul_f32 v[20:21], v[20:21], v[188:189] op_sel_hi:[1,0]
	v_pk_mul_f32 v[22:23], v[22:23], v[188:189] op_sel_hi:[1,0]
	v_pk_mul_f32 v[16:17], v[16:17], v[188:189] op_sel_hi:[1,0]
	v_pk_mul_f32 v[18:19], v[18:19], v[188:189] op_sel_hi:[1,0]
	s_waitcnt vmcnt(10)
	v_pk_mul_f32 v[234:235], v[20:21], v[152:153]
	v_pk_mul_f32 v[236:237], v[22:23], v[154:155]
	v_pk_mul_f32 v[238:239], v[16:17], v[156:157]
	v_pk_mul_f32 v[240:241], v[18:19], v[158:159]
	v_pk_fma_f32 v[234:235], v[28:29], v[144:145], v[234:235] neg_lo:[0,0,1] neg_hi:[0,0,1]
	v_pk_fma_f32 v[236:237], v[30:31], v[146:147], v[236:237] neg_lo:[0,0,1] neg_hi:[0,0,1]
	v_pk_fma_f32 v[238:239], v[24:25], v[148:149], v[238:239] neg_lo:[0,0,1] neg_hi:[0,0,1]
	v_pk_fma_f32 v[240:241], v[26:27], v[150:151], v[240:241] neg_lo:[0,0,1] neg_hi:[0,0,1]
	v_pk_mul_f32 v[152:153], v[28:29], v[152:153]
	v_pk_mul_f32 v[154:155], v[30:31], v[154:155]
	v_pk_mul_f32 v[156:157], v[24:25], v[156:157]
	v_pk_mul_f32 v[158:159], v[26:27], v[158:159]
	v_pk_fma_f32 v[152:153], v[20:21], v[144:145], v[152:153]
	v_pk_fma_f32 v[154:155], v[22:23], v[146:147], v[154:155]
	v_pk_fma_f32 v[156:157], v[16:17], v[148:149], v[156:157]
	v_pk_fma_f32 v[158:159], v[18:19], v[150:151], v[158:159]
	v_pk_mul_f32 v[234:235], v[234:235], s[30:31]
	v_pk_mul_f32 v[236:237], v[236:237], s[30:31]
	v_pk_mul_f32 v[238:239], v[238:239], s[30:31]
	v_pk_mul_f32 v[240:241], v[240:241], s[30:31]
	v_pk_mul_f32 v[152:153], v[152:153], s[30:31]
	v_pk_mul_f32 v[154:155], v[154:155], s[30:31]
	v_pk_mul_f32 v[156:157], v[156:157], s[30:31]
	v_pk_mul_f32 v[158:159], v[158:159], s[30:31]
	v_cvt_pk_bf16_f32 v28, v234, v235
	v_cvt_pk_bf16_f32 v29, v236, v237
	v_cvt_pk_bf16_f32 v30, v238, v239
	v_cvt_pk_bf16_f32 v31, v240, v241
	global_store_dwordx4 v214, v[28:31], s[16:17]
	v_cvt_pk_bf16_f32 v20, v152, v153
	v_cvt_pk_bf16_f32 v21, v154, v155
	v_cvt_pk_bf16_f32 v22, v156, v157
	v_cvt_pk_bf16_f32 v23, v158, v159
	global_store_dwordx4 v214, v[20:23], s[16:17] offset:64
	s_add_u32 s16, s16, 0x4000
	s_addc_u32 s17, s17, 0
	v_pk_mul_f32 v[12:13], v[12:13], v[190:191] op_sel_hi:[1,0]
	v_pk_mul_f32 v[14:15], v[14:15], v[190:191] op_sel_hi:[1,0]
	v_pk_mul_f32 v[8:9], v[8:9], v[190:191] op_sel_hi:[1,0]
	v_pk_mul_f32 v[10:11], v[10:11], v[190:191] op_sel_hi:[1,0]
	v_pk_mul_f32 v[4:5], v[4:5], v[190:191] op_sel_hi:[1,0]
	v_pk_mul_f32 v[6:7], v[6:7], v[190:191] op_sel_hi:[1,0]
	v_pk_mul_f32 v[0:1], v[0:1], v[190:191] op_sel_hi:[1,0]
	v_pk_mul_f32 v[2:3], v[2:3], v[190:191] op_sel_hi:[1,0]
	s_waitcnt vmcnt(6)
	v_pk_mul_f32 v[234:235], v[4:5], v[168:169]
	v_pk_mul_f32 v[236:237], v[6:7], v[170:171]
	v_pk_mul_f32 v[238:239], v[0:1], v[172:173]
	v_pk_mul_f32 v[240:241], v[2:3], v[174:175]
	v_pk_fma_f32 v[234:235], v[12:13], v[160:161], v[234:235] neg_lo:[0,0,1] neg_hi:[0,0,1]
	v_pk_fma_f32 v[236:237], v[14:15], v[162:163], v[236:237] neg_lo:[0,0,1] neg_hi:[0,0,1]
	v_pk_fma_f32 v[238:239], v[8:9], v[164:165], v[238:239] neg_lo:[0,0,1] neg_hi:[0,0,1]
	v_pk_fma_f32 v[240:241], v[10:11], v[166:167], v[240:241] neg_lo:[0,0,1] neg_hi:[0,0,1]
	v_pk_mul_f32 v[168:169], v[12:13], v[168:169]
	v_pk_mul_f32 v[170:171], v[14:15], v[170:171]
	v_pk_mul_f32 v[172:173], v[8:9], v[172:173]
	v_pk_mul_f32 v[174:175], v[10:11], v[174:175]
	v_pk_fma_f32 v[168:169], v[4:5], v[160:161], v[168:169]
	v_pk_fma_f32 v[170:171], v[6:7], v[162:163], v[170:171]
	v_pk_fma_f32 v[172:173], v[0:1], v[164:165], v[172:173]
	v_pk_fma_f32 v[174:175], v[2:3], v[166:167], v[174:175]
	v_pk_mul_f32 v[234:235], v[234:235], s[30:31]
	v_pk_mul_f32 v[236:237], v[236:237], s[30:31]
	v_pk_mul_f32 v[238:239], v[238:239], s[30:31]
	v_pk_mul_f32 v[240:241], v[240:241], s[30:31]
	v_pk_mul_f32 v[168:169], v[168:169], s[30:31]
	v_pk_mul_f32 v[170:171], v[170:171], s[30:31]
	v_pk_mul_f32 v[172:173], v[172:173], s[30:31]
	v_pk_mul_f32 v[174:175], v[174:175], s[30:31]
	v_cvt_pk_bf16_f32 v12, v234, v235
	v_cvt_pk_bf16_f32 v13, v236, v237
	v_cvt_pk_bf16_f32 v14, v238, v239
	v_cvt_pk_bf16_f32 v15, v240, v241
	global_store_dwordx4 v214, v[12:15], s[16:17]
	v_cvt_pk_bf16_f32 v4, v168, v169
	v_cvt_pk_bf16_f32 v5, v170, v171
	v_cvt_pk_bf16_f32 v6, v172, v173
	v_cvt_pk_bf16_f32 v7, v174, v175
	global_store_dwordx4 v214, v[4:7], s[16:17] offset:64
	s_branch .LBB0_580
; __device__ __forceinline__ u32x4 pk8(f32x4 a, f32x4 b) { u32x4 w; w.x = pk2(a[0], a[1]); w.y = pk2(a[2], a[3]); w.z = pk2(b[0], b[1]); w.w = pk2(b[2], b[3]); return w; }
;     __device__ __forceinline__ void operator()(const f32x4 (&acc)[2][2][4][2], const pg8::Unit& u, int wr, int wc, int fr_, int fq_) const {
;     ...
;                 const int k = it - 2, ai = k >> 2, m = k & 3, row = row0 + ai * 128 + m * 16;
;                 float sq = (ld[k].ss[0] + ld[k].ss[1]) + (ld[k].ss[2] + ld[k].ss[3]); sq += __shfl_xor(sq, 16); sq += __shfl_xor(sq, 32);
;                 const float rs = __builtin_amdgcn_rsqf(sq * (1.f / 1024.f) + EPS);
;                 const f32x4 a0 = acc[ai][0][m][0] * rs, a1 = acc[ai][0][m][1] * rs, b0 = acc[ai][1][m][0] * rs, b1 = acc[ai][1][m][1] * rs;
;                 if (rope) {
;                     const f32x4 c0 = ld[k].c0, c1 = ld[k].c1, s0 = ld[k].s0, s1 = ld[k].s1;
;                     f32x4 o1a = a0 * c0 - b0 * s0, o1b = a1 * c1 - b1 * s1, o2a = b0 * c0 + a0 * s0, o2b = b1 * c1 + a1 * s1;
;                     if (pn < 2) {
;                         o1a *= QS; o1b *= QS; o2a *= QS; o2b *= QS;
;                         bf16_t* q = Q + (size_t)row * 512 + (4 * pn + wc) * 64 + fq * 8;
;                         gst<u32x4>(q, pk8(o1a, o1b)); gst<u32x4>(q + 32, pk8(o2a, o2b));
;                     } else {
;                         bf16_t* kk = K + (size_t)row * 128 + wc * 64 + fq * 8;
;                         gst<u32x4>(kk, pk8(o1a, o1b)); gst<u32x4>(kk + 32, pk8(o2a, o2b));
;                         const bool smp = row >= NPR; const bool wr_out = smp || (row & 2047) >= 1920;
;                         const size_t kofs = smp ? O_NKS + ((size_t)(L * 128 + ((row - NPR) >> 2)) * 128 + 124 + (row & 3)) * 128 : O_NKP + ((size_t)(L * 8 + (row >> 11)) * 128 + ((row & 2047) - 1920)) * 128;
;                         if (wr_out) { float* ko = out + kofs + wc * 64 + fq * 8; gst<f32x4>(ko, o1a); gst<f32x4>(ko + 4, o1b); gst<f32x4>(ko + 32, o2a); gst<f32x4>(ko + 36, o2b); }
.Lme_kvpath:
	s_cmp_gt_u32 s93, 127
	s_cbranch_scc1 .Lme_vpath
	s_mov_b32 s9, 0
	s_cmp_gt_i32 s4, 63
	s_cbranch_scc1 .Lme_kvsmp_k
	s_and_b32 s5, s4, 7
	s_cmp_eq_u32 s5, 7
	s_cbranch_scc0 .Lme_kvfd_k
	s_mov_b32 s9, 2
	v_and_b32_e32 v216, 15, v248
	v_lshlrev_b32_e32 v216, 9, v216
	v_lshl_add_u32 v216, v211, 5, v216
	s_lshl_b32 s5, s20, 3
	s_lshr_b32 s18, s4, 3
	s_add_i32 s5, s5, s18
	s_lshl_b32 s5, s5, 16
	s_lshl_b32 s18, s89, 9
	s_add_i32 s5, s5, s18
	s_add_u32 s5, s5, 0x4200000
	s_branch .Lme_kvfb_k
.Lme_kvsmp_k:
	s_mov_b32 s9, 1
	v_and_b32_e32 v216, 15, v248
	v_lshrrev_b32_e32 v217, 2, v216
	v_and_b32_e32 v216, 3, v216
	v_lshlrev_b32_e32 v216, 9, v216
	v_lshl_add_u32 v216, v217, 16, v216
	v_lshl_add_u32 v216, v211, 5, v216
	s_add_i32 s5, s4, -64
	s_lshl_b32 s5, s5, 6
	s_lshr_b32 s18, s89, 2
	s_add_i32 s5, s5, s18
	s_lshl_b32 s5, s5, 16
	s_lshl_b32 s18, s20, 23
	s_add_i32 s5, s5, s18
	s_add_u32 s5, s5, 0x462f800
.Lme_kvfb_k:
	s_lshl_b32 s18, s93, 2
	s_add_i32 s5, s5, s18
	s_add_u32 s18, s28, s5
	s_addc_u32 s19, s29, 0
.Lme_kvfd_k:
	global_load_dwordx4 v[144:147], v252, s[12:13]
	global_load_dwordx4 v[148:151], v252, s[12:13] offset:16
	global_load_dwordx4 v[152:155], v252, s[12:13] offset:128
	global_load_dwordx4 v[156:159], v252, s[12:13] offset:144
	v_add_u32_e32 v252, s7, v252
	global_load_dwordx4 v[160:163], v252, s[12:13]
	global_load_dwordx4 v[164:167], v252, s[12:13] offset:16
	global_load_dwordx4 v[168:171], v252, s[12:13] offset:128
	global_load_dwordx4 v[172:175], v252, s[12:13] offset:144
	v_add_u32_e32 v252, s8, v252
	v_pk_mul_f32 v[132:133], v[132:133], v[176:177] op_sel_hi:[1,0]
	v_pk_mul_f32 v[134:135], v[134:135], v[176:177] op_sel_hi:[1,0]
	v_pk_mul_f32 v[128:129], v[128:129], v[176:177] op_sel_hi:[1,0]
	v_pk_mul_f32 v[130:131], v[130:131], v[176:177] op_sel_hi:[1,0]
	v_pk_mul_f32 v[116:117], v[116:117], v[176:177] op_sel_hi:[1,0]
	v_pk_mul_f32 v[118:119], v[118:119], v[176:177] op_sel_hi:[1,0]
	v_pk_mul_f32 v[112:113], v[112:113], v[176:177] op_sel_hi:[1,0]
	v_pk_mul_f32 v[114:115], v[114:115], v[176:177] op_sel_hi:[1,0]
	s_waitcnt vmcnt(12)
	v_pk_mul_f32 v[234:235], v[116:117], v[104:105]
	v_pk_mul_f32 v[236:237], v[118:119], v[106:107]
	v_pk_mul_f32 v[238:239], v[112:113], v[108:109]
	v_pk_mul_f32 v[240:241], v[114:115], v[110:111]
	v_pk_fma_f32 v[234:235], v[132:133], v[96:97], v[234:235] neg_lo:[0,0,1] neg_hi:[0,0,1]
	v_pk_fma_f32 v[236:237], v[134:135], v[98:99], v[236:237] neg_lo:[0,0,1] neg_hi:[0,0,1]
	v_pk_fma_f32 v[238:239], v[128:129], v[100:101], v[238:239] neg_lo:[0,0,1] neg_hi:[0,0,1]
	v_pk_fma_f32 v[240:241], v[130:131], v[102:103], v[240:241] neg_lo:[0,0,1] neg_hi:[0,0,1]
	v_pk_mul_f32 v[104:105], v[132:133], v[104:105]
	v_pk_mul_f32 v[106:107], v[134:135], v[106:107]
	v_pk_mul_f32 v[108:109], v[128:129], v[108:109]
	v_pk_mul_f32 v[110:111], v[130:131], v[110:111]
	v_pk_fma_f32 v[104:105], v[116:117], v[96:97], v[104:105]
	v_pk_fma_f32 v[106:107], v[118:119], v[98:99], v[106:107]
	v_pk_fma_f32 v[108:109], v[112:113], v[100:101], v[108:109]
	v_pk_fma_f32 v[110:111], v[114:115], v[102:103], v[110:111]
	s_cmp_eq_u32 s9, 1
	s_cbranch_scc0 .Lme_kvn_k_0
.Lme_kvs_k_0:
	global_store_dwordx4 v216, v[234:237], s[18:19]
	global_store_dwordx4 v216, v[238:241], s[18:19] offset:16
	global_store_dwordx4 v216, v[104:107], s[18:19] offset:128
	global_store_dwordx4 v216, v[108:111], s[18:19] offset:144
.Lme_kvn_k_0:
	v_cvt_pk_bf16_f32 v132, v234, v235
	v_cvt_pk_bf16_f32 v133, v236, v237
	v_cvt_pk_bf16_f32 v134, v238, v239
	v_cvt_pk_bf16_f32 v135, v240, v241
	global_store_dwordx4 v215, v[132:135], s[16:17]
	v_cvt_pk_bf16_f32 v116, v104, v105
	v_cvt_pk_bf16_f32 v117, v106, v107
	v_cvt_pk_bf16_f32 v118, v108, v109
	v_cvt_pk_bf16_f32 v119, v110, v111
	global_store_dwordx4 v215, v[116:119], s[16:17] offset:64
	s_add_u32 s16, s16, 0x1000
	s_addc_u32 s17, s17, 0
	s_cmp_eq_u32 s9, 1
	s_cselect_b32 s5, 0x40000, 0
	s_add_u32 s18, s18, s5
	s_addc_u32 s19, s19, 0
	global_load_dwordx4 v[96:99], v252, s[12:13]
	global_load_dwordx4 v[100:103], v252, s[12:13] offset:16
	global_load_dwordx4 v[104:107], v252, s[12:13] offset:128
	global_load_dwordx4 v[108:111], v252, s[12:13] offset:144
	v_add_u32_e32 v252, s7, v252
	v_pk_mul_f32 v[140:141], v[140:141], v[178:179] op_sel_hi:[1,0]
	v_pk_mul_f32 v[142:143], v[142:143], v[178:179] op_sel_hi:[1,0]
	v_pk_mul_f32 v[136:137], v[136:137], v[178:179] op_sel_hi:[1,0]
	v_pk_mul_f32 v[138:139], v[138:139], v[178:179] op_sel_hi:[1,0]
	v_pk_mul_f32 v[124:125], v[124:125], v[178:179] op_sel_hi:[1,0]
	v_pk_mul_f32 v[126:127], v[126:127], v[178:179] op_sel_hi:[1,0]
	v_pk_mul_f32 v[120:121], v[120:121], v[178:179] op_sel_hi:[1,0]
	v_pk_mul_f32 v[122:123], v[122:123], v[178:179] op_sel_hi:[1,0]
	s_waitcnt vmcnt(14)
	v_pk_mul_f32 v[234:235], v[124:125], v[226:227]
	v_pk_mul_f32 v[236:237], v[126:127], v[228:229]
	v_pk_mul_f32 v[238:239], v[120:121], v[230:231]
	v_pk_mul_f32 v[240:241], v[122:123], v[232:233]
	v_pk_fma_f32 v[234:235], v[140:141], v[218:219], v[234:235] neg_lo:[0,0,1] neg_hi:[0,0,1]
	v_pk_fma_f32 v[236:237], v[142:143], v[220:221], v[236:237] neg_lo:[0,0,1] neg_hi:[0,0,1]
	v_pk_fma_f32 v[238:239], v[136:137], v[222:223], v[238:239] neg_lo:[0,0,1] neg_hi:[0,0,1]
	v_pk_fma_f32 v[240:241], v[138:139], v[224:225], v[240:241] neg_lo:[0,0,1] neg_hi:[0,0,1]
	v_pk_mul_f32 v[226:227], v[140:141], v[226:227]
	v_pk_mul_f32 v[228:229], v[142:143], v[228:229]
	v_pk_mul_f32 v[230:231], v[136:137], v[230:231]
	v_pk_mul_f32 v[232:233], v[138:139], v[232:233]
	v_pk_fma_f32 v[226:227], v[124:125], v[218:219], v[226:227]
	v_pk_fma_f32 v[228:229], v[126:127], v[220:221], v[228:229]
	v_pk_fma_f32 v[230:231], v[120:121], v[222:223], v[230:231]
	v_pk_fma_f32 v[232:233], v[122:123], v[224:225], v[232:233]
	s_cmp_eq_u32 s9, 1
	s_cbranch_scc0 .Lme_kvn_k_1
; __device__ __forceinline__ u32x4 pk8(f32x4 a, f32x4 b) { u32x4 w; w.x = pk2(a[0], a[1]); w.y = pk2(a[2], a[3]); w.z = pk2(b[0], b[1]); w.w = pk2(b[2], b[3]); return w; }
;     __device__ __forceinline__ void operator()(const f32x4 (&acc)[2][2][4][2], const pg8::Unit& u, int wr, int wc, int fr_, int fq_) const {
;     ...
;                 const int k = it - 2, ai = k >> 2, m = k & 3, row = row0 + ai * 128 + m * 16;
;                 float sq = (ld[k].ss[0] + ld[k].ss[1]) + (ld[k].ss[2] + ld[k].ss[3]); sq += __shfl_xor(sq, 16); sq += __shfl_xor(sq, 32);
;                 const float rs = __builtin_amdgcn_rsqf(sq * (1.f / 1024.f) + EPS);
;                 const f32x4 a0 = acc[ai][0][m][0] * rs, a1 = acc[ai][0][m][1] * rs, b0 = acc[ai][1][m][0] * rs, b1 = acc[ai][1][m][1] * rs;
;                 if (rope) {
;                     const f32x4 c0 = ld[k].c0, c1 = ld[k].c1, s0 = ld[k].s0, s1 = ld[k].s1;
;                     f32x4 o1a = a0 * c0 - b0 * s0, o1b = a1 * c1 - b1 * s1, o2a = b0 * c0 + a0 * s0, o2b = b1 * c1 + a1 * s1;
;                     if (pn < 2) {
;                         o1a *= QS; o1b *= QS; o2a *= QS; o2b *= QS;
;                         bf16_t* q = Q + (size_t)row * 512 + (4 * pn + wc) * 64 + fq * 8;
;                         gst<u32x4>(q, pk8(o1a, o1b)); gst<u32x4>(q + 32, pk8(o2a, o2b));
;                     } else {
;                         bf16_t* kk = K + (size_t)row * 128 + wc * 64 + fq * 8;
;                         gst<u32x4>(kk, pk8(o1a, o1b)); gst<u32x4>(kk + 32, pk8(o2a, o2b));
;                         const bool smp = row >= NPR; const bool wr_out = smp || (row & 2047) >= 1920;
;                         const size_t kofs = smp ? O_NKS + ((size_t)(L * 128 + ((row - NPR) >> 2)) * 128 + 124 + (row & 3)) * 128 : O_NKP + ((size_t)(L * 8 + (row >> 11)) * 128 + ((row & 2047) - 1920)) * 128;
;                         if (wr_out) { float* ko = out + kofs + wc * 64 + fq * 8; gst<f32x4>(ko, o1a); gst<f32x4>(ko + 4, o1b); gst<f32x4>(ko + 32, o2a); gst<f32x4>(ko + 36, o2b); }
.Lme_kvs_k_1:
	global_store_dwordx4 v216, v[234:237], s[18:19]
	global_store_dwordx4 v216, v[238:241], s[18:19] offset:16
	global_store_dwordx4 v216, v[226:229], s[18:19] offset:128
	global_store_dwordx4 v216, v[230:233], s[18:19] offset:144
.Lme_kvn_k_1:
	v_cvt_pk_bf16_f32 v140, v234, v235
	v_cvt_pk_bf16_f32 v141, v236, v237
	v_cvt_pk_bf16_f32 v142, v238, v239
	v_cvt_pk_bf16_f32 v143, v240, v241
	global_store_dwordx4 v215, v[140:143], s[16:17]
	v_cvt_pk_bf16_f32 v124, v226, v227
	v_cvt_pk_bf16_f32 v125, v228, v229
	v_cvt_pk_bf16_f32 v126, v230, v231
	v_cvt_pk_bf16_f32 v127, v232, v233
	global_store_dwordx4 v215, v[124:127], s[16:17] offset:64
	s_add_u32 s16, s16, 0x1000
	s_addc_u32 s17, s17, 0
	s_cmp_eq_u32 s9, 1
	s_cselect_b32 s5, 0x40000, 0
	s_add_u32 s18, s18, s5
	s_addc_u32 s19, s19, 0
	global_load_dwordx4 v[218:221], v252, s[12:13]
	global_load_dwordx4 v[222:225], v252, s[12:13] offset:16
	global_load_dwordx4 v[226:229], v252, s[12:13] offset:128
	global_load_dwordx4 v[230:233], v252, s[12:13] offset:144
	v_add_u32_e32 v252, s7, v252
	v_pk_mul_f32 v[92:93], v[92:93], v[180:181] op_sel_hi:[1,0]
	v_pk_mul_f32 v[94:95], v[94:95], v[180:181] op_sel_hi:[1,0]
	v_pk_mul_f32 v[88:89], v[88:89], v[180:181] op_sel_hi:[1,0]
	v_pk_mul_f32 v[90:91], v[90:91], v[180:181] op_sel_hi:[1,0]
	v_pk_mul_f32 v[84:85], v[84:85], v[180:181] op_sel_hi:[1,0]
	v_pk_mul_f32 v[86:87], v[86:87], v[180:181] op_sel_hi:[1,0]
	v_pk_mul_f32 v[80:81], v[80:81], v[180:181] op_sel_hi:[1,0]
	v_pk_mul_f32 v[82:83], v[82:83], v[180:181] op_sel_hi:[1,0]
	s_waitcnt vmcnt(16)
	v_pk_mul_f32 v[234:235], v[84:85], v[152:153]
	v_pk_mul_f32 v[236:237], v[86:87], v[154:155]
	v_pk_mul_f32 v[238:239], v[80:81], v[156:157]
	v_pk_mul_f32 v[240:241], v[82:83], v[158:159]
	v_pk_fma_f32 v[234:235], v[92:93], v[144:145], v[234:235] neg_lo:[0,0,1] neg_hi:[0,0,1]
	v_pk_fma_f32 v[236:237], v[94:95], v[146:147], v[236:237] neg_lo:[0,0,1] neg_hi:[0,0,1]
	v_pk_fma_f32 v[238:239], v[88:89], v[148:149], v[238:239] neg_lo:[0,0,1] neg_hi:[0,0,1]
	v_pk_fma_f32 v[240:241], v[90:91], v[150:151], v[240:241] neg_lo:[0,0,1] neg_hi:[0,0,1]
	v_pk_mul_f32 v[152:153], v[92:93], v[152:153]
	v_pk_mul_f32 v[154:155], v[94:95], v[154:155]
	v_pk_mul_f32 v[156:157], v[88:89], v[156:157]
	v_pk_mul_f32 v[158:159], v[90:91], v[158:159]
	v_pk_fma_f32 v[152:153], v[84:85], v[144:145], v[152:153]
	v_pk_fma_f32 v[154:155], v[86:87], v[146:147], v[154:155]
	v_pk_fma_f32 v[156:157], v[80:81], v[148:149], v[156:157]
	v_pk_fma_f32 v[158:159], v[82:83], v[150:151], v[158:159]
	s_cmp_eq_u32 s9, 1
	s_cbranch_scc0 .Lme_kvn_k_2
.Lme_kvs_k_2:
	global_store_dwordx4 v216, v[234:237], s[18:19]
	global_store_dwordx4 v216, v[238:241], s[18:19] offset:16
	global_store_dwordx4 v216, v[152:155], s[18:19] offset:128
	global_store_dwordx4 v216, v[156:159], s[18:19] offset:144
; __device__ __forceinline__ u32x4 pk8(f32x4 a, f32x4 b) { u32x4 w; w.x = pk2(a[0], a[1]); w.y = pk2(a[2], a[3]); w.z = pk2(b[0], b[1]); w.w = pk2(b[2], b[3]); return w; }
;     __device__ __forceinline__ void operator()(const f32x4 (&acc)[2][2][4][2], const pg8::Unit& u, int wr, int wc, int fr_, int fq_) const {
;     ...
;                 const int k = it - 2, ai = k >> 2, m = k & 3, row = row0 + ai * 128 + m * 16;
;                 float sq = (ld[k].ss[0] + ld[k].ss[1]) + (ld[k].ss[2] + ld[k].ss[3]); sq += __shfl_xor(sq, 16); sq += __shfl_xor(sq, 32);
;                 const float rs = __builtin_amdgcn_rsqf(sq * (1.f / 1024.f) + EPS);
;                 const f32x4 a0 = acc[ai][0][m][0] * rs, a1 = acc[ai][0][m][1] * rs, b0 = acc[ai][1][m][0] * rs, b1 = acc[ai][1][m][1] * rs;
;                 if (rope) {
;                     const f32x4 c0 = ld[k].c0, c1 = ld[k].c1, s0 = ld[k].s0, s1 = ld[k].s1;
;                     f32x4 o1a = a0 * c0 - b0 * s0, o1b = a1 * c1 - b1 * s1, o2a = b0 * c0 + a0 * s0, o2b = b1 * c1 + a1 * s1;
;                     if (pn < 2) {
;                         o1a *= QS; o1b *= QS; o2a *= QS; o2b *= QS;
;                         bf16_t* q = Q + (size_t)row * 512 + (4 * pn + wc) * 64 + fq * 8;
;                         gst<u32x4>(q, pk8(o1a, o1b)); gst<u32x4>(q + 32, pk8(o2a, o2b));
;                     } else {
;                         bf16_t* kk = K + (size_t)row * 128 + wc * 64 + fq * 8;
;                         gst<u32x4>(kk, pk8(o1a, o1b)); gst<u32x4>(kk + 32, pk8(o2a, o2b));
;                         const bool smp = row >= NPR; const bool wr_out = smp || (row & 2047) >= 1920;
;                         const size_t kofs = smp ? O_NKS + ((size_t)(L * 128 + ((row - NPR) >> 2)) * 128 + 124 + (row & 3)) * 128 : O_NKP + ((size_t)(L * 8 + (row >> 11)) * 128 + ((row & 2047) - 1920)) * 128;
;                         if (wr_out) { float* ko = out + kofs + wc * 64 + fq * 8; gst<f32x4>(ko, o1a); gst<f32x4>(ko + 4, o1b); gst<f32x4>(ko + 32, o2a); gst<f32x4>(ko + 36, o2b); }
.Lme_kvn_k_2:
	v_cvt_pk_bf16_f32 v92, v234, v235
	v_cvt_pk_bf16_f32 v93, v236, v237
	v_cvt_pk_bf16_f32 v94, v238, v239
	v_cvt_pk_bf16_f32 v95, v240, v241
	global_store_dwordx4 v215, v[92:95], s[16:17]
	v_cvt_pk_bf16_f32 v84, v152, v153
	v_cvt_pk_bf16_f32 v85, v154, v155
	v_cvt_pk_bf16_f32 v86, v156, v157
	v_cvt_pk_bf16_f32 v87, v158, v159
	global_store_dwordx4 v215, v[84:87], s[16:17] offset:64
	s_add_u32 s16, s16, 0x1000
	s_addc_u32 s17, s17, 0
	s_cmp_eq_u32 s9, 1
	s_cselect_b32 s5, 0x40000, 0
	s_add_u32 s18, s18, s5
	s_addc_u32 s19, s19, 0
	global_load_dwordx4 v[144:147], v252, s[12:13]
	global_load_dwordx4 v[148:151], v252, s[12:13] offset:16
	global_load_dwordx4 v[152:155], v252, s[12:13] offset:128
	global_load_dwordx4 v[156:159], v252, s[12:13] offset:144
	v_add_u32_e32 v252, s7, v252
	v_pk_mul_f32 v[76:77], v[76:77], v[182:183] op_sel_hi:[1,0]
	v_pk_mul_f32 v[78:79], v[78:79], v[182:183] op_sel_hi:[1,0]
	v_pk_mul_f32 v[72:73], v[72:73], v[182:183] op_sel_hi:[1,0]
	v_pk_mul_f32 v[74:75], v[74:75], v[182:183] op_sel_hi:[1,0]
	v_pk_mul_f32 v[68:69], v[68:69], v[182:183] op_sel_hi:[1,0]
	v_pk_mul_f32 v[70:71], v[70:71], v[182:183] op_sel_hi:[1,0]
	v_pk_mul_f32 v[64:65], v[64:65], v[182:183] op_sel_hi:[1,0]
	v_pk_mul_f32 v[66:67], v[66:67], v[182:183] op_sel_hi:[1,0]
	s_waitcnt vmcnt(18)
	v_pk_mul_f32 v[234:235], v[68:69], v[168:169]
	v_pk_mul_f32 v[236:237], v[70:71], v[170:171]
	v_pk_mul_f32 v[238:239], v[64:65], v[172:173]
	v_pk_mul_f32 v[240:241], v[66:67], v[174:175]
	v_pk_fma_f32 v[234:235], v[76:77], v[160:161], v[234:235] neg_lo:[0,0,1] neg_hi:[0,0,1]
	v_pk_fma_f32 v[236:237], v[78:79], v[162:163], v[236:237] neg_lo:[0,0,1] neg_hi:[0,0,1]
	v_pk_fma_f32 v[238:239], v[72:73], v[164:165], v[238:239] neg_lo:[0,0,1] neg_hi:[0,0,1]
	v_pk_fma_f32 v[240:241], v[74:75], v[166:167], v[240:241] neg_lo:[0,0,1] neg_hi:[0,0,1]
	v_pk_mul_f32 v[168:169], v[76:77], v[168:169]
	v_pk_mul_f32 v[170:171], v[78:79], v[170:171]
	v_pk_mul_f32 v[172:173], v[72:73], v[172:173]
	v_pk_mul_f32 v[174:175], v[74:75], v[174:175]
	v_pk_fma_f32 v[168:169], v[68:69], v[160:161], v[168:169]
	v_pk_fma_f32 v[170:171], v[70:71], v[162:163], v[170:171]
	v_pk_fma_f32 v[172:173], v[64:65], v[164:165], v[172:173]
	v_pk_fma_f32 v[174:175], v[66:67], v[166:167], v[174:175]
	s_cmp_eq_u32 s9, 1
	s_cbranch_scc0 .Lme_kvn_k_3
.Lme_kvs_k_3:
	global_store_dwordx4 v216, v[234:237], s[18:19]
	global_store_dwordx4 v216, v[238:241], s[18:19] offset:16
	global_store_dwordx4 v216, v[168:171], s[18:19] offset:128
	global_store_dwordx4 v216, v[172:175], s[18:19] offset:144
.Lme_kvn_k_3:
	v_cvt_pk_bf16_f32 v76, v234, v235
	v_cvt_pk_bf16_f32 v77, v236, v237
	v_cvt_pk_bf16_f32 v78, v238, v239
	v_cvt_pk_bf16_f32 v79, v240, v241
	global_store_dwordx4 v215, v[76:79], s[16:17]
	v_cvt_pk_bf16_f32 v68, v168, v169
	v_cvt_pk_bf16_f32 v69, v170, v171
	v_cvt_pk_bf16_f32 v70, v172, v173
	v_cvt_pk_bf16_f32 v71, v174, v175
	global_store_dwordx4 v215, v[68:71], s[16:17] offset:64
	s_add_u32 s16, s16, 0x5000
	s_addc_u32 s17, s17, 0
	s_cmp_eq_u32 s9, 1
	s_cselect_b32 s5, 0x140000, 0
	s_add_u32 s18, s18, s5
	s_addc_u32 s19, s19, 0
	global_load_dwordx4 v[160:163], v252, s[12:13]
	global_load_dwordx4 v[164:167], v252, s[12:13] offset:16
	global_load_dwordx4 v[168:171], v252, s[12:13] offset:128
	global_load_dwordx4 v[172:175], v252, s[12:13] offset:144
	v_pk_mul_f32 v[60:61], v[60:61], v[184:185] op_sel_hi:[1,0]
	v_pk_mul_f32 v[62:63], v[62:63], v[184:185] op_sel_hi:[1,0]
	v_pk_mul_f32 v[56:57], v[56:57], v[184:185] op_sel_hi:[1,0]
	v_pk_mul_f32 v[58:59], v[58:59], v[184:185] op_sel_hi:[1,0]
	v_pk_mul_f32 v[52:53], v[52:53], v[184:185] op_sel_hi:[1,0]
	v_pk_mul_f32 v[54:55], v[54:55], v[184:185] op_sel_hi:[1,0]
	v_pk_mul_f32 v[48:49], v[48:49], v[184:185] op_sel_hi:[1,0]
	v_pk_mul_f32 v[50:51], v[50:51], v[184:185] op_sel_hi:[1,0]
	s_waitcnt vmcnt(18)
	v_pk_mul_f32 v[234:235], v[52:53], v[104:105]
	v_pk_mul_f32 v[236:237], v[54:55], v[106:107]
	v_pk_mul_f32 v[238:239], v[48:49], v[108:109]
	v_pk_mul_f32 v[240:241], v[50:51], v[110:111]
	v_pk_fma_f32 v[234:235], v[60:61], v[96:97], v[234:235] neg_lo:[0,0,1] neg_hi:[0,0,1]
	v_pk_fma_f32 v[236:237], v[62:63], v[98:99], v[236:237] neg_lo:[0,0,1] neg_hi:[0,0,1]
	v_pk_fma_f32 v[238:239], v[56:57], v[100:101], v[238:239] neg_lo:[0,0,1] neg_hi:[0,0,1]
	v_pk_fma_f32 v[240:241], v[58:59], v[102:103], v[240:241] neg_lo:[0,0,1] neg_hi:[0,0,1]
	v_pk_mul_f32 v[104:105], v[60:61], v[104:105]
	v_pk_mul_f32 v[106:107], v[62:63], v[106:107]
	v_pk_mul_f32 v[108:109], v[56:57], v[108:109]
	v_pk_mul_f32 v[110:111], v[58:59], v[110:111]
	v_pk_fma_f32 v[104:105], v[52:53], v[96:97], v[104:105]
	v_pk_fma_f32 v[106:107], v[54:55], v[98:99], v[106:107]
	v_pk_fma_f32 v[108:109], v[48:49], v[100:101], v[108:109]
	v_pk_fma_f32 v[110:111], v[50:51], v[102:103], v[110:111]
	s_cmp_eq_u32 s9, 1
	s_cbranch_scc1 .Lme_kvs_k_4
	s_cmp_eq_u32 s9, 2
	s_cbranch_scc0 .Lme_kvn_k_4

; __device__ __forceinline__ u32x4 pk8(f32x4 a, f32x4 b) { u32x4 w; w.x = pk2(a[0], a[1]); w.y = pk2(a[2], a[3]); w.z = pk2(b[0], b[1]); w.w = pk2(b[2], b[3]); return w; }
;     __device__ __forceinline__ void operator()(const f32x4 (&acc)[2][2][4][2], const pg8::Unit& u, int wr, int wc, int fr_, int fq_) const {
;     ...
;                 const int k = it - 2, ai = k >> 2, m = k & 3, row = row0 + ai * 128 + m * 16;
;                 float sq = (ld[k].ss[0] + ld[k].ss[1]) + (ld[k].ss[2] + ld[k].ss[3]); sq += __shfl_xor(sq, 16); sq += __shfl_xor(sq, 32);
;                 const float rs = __builtin_amdgcn_rsqf(sq * (1.f / 1024.f) + EPS);
;                 const f32x4 a0 = acc[ai][0][m][0] * rs, a1 = acc[ai][0][m][1] * rs, b0 = acc[ai][1][m][0] * rs, b1 = acc[ai][1][m][1] * rs;
;                 if (rope) {
;                     const f32x4 c0 = ld[k].c0, c1 = ld[k].c1, s0 = ld[k].s0, s1 = ld[k].s1;
;                     f32x4 o1a = a0 * c0 - b0 * s0, o1b = a1 * c1 - b1 * s1, o2a = b0 * c0 + a0 * s0, o2b = b1 * c1 + a1 * s1;
;                     if (pn < 2) {
;                         o1a *= QS; o1b *= QS; o2a *= QS; o2b *= QS;
;                         bf16_t* q = Q + (size_t)row * 512 + (4 * pn + wc) * 64 + fq * 8;
;                         gst<u32x4>(q, pk8(o1a, o1b)); gst<u32x4>(q + 32, pk8(o2a, o2b));
;                     } else {
;                         bf16_t* kk = K + (size_t)row * 128 + wc * 64 + fq * 8;
;                         gst<u32x4>(kk, pk8(o1a, o1b)); gst<u32x4>(kk + 32, pk8(o2a, o2b));
;                         const bool smp = row >= NPR; const bool wr_out = smp || (row & 2047) >= 1920;
;                         const size_t kofs = smp ? O_NKS + ((size_t)(L * 128 + ((row - NPR) >> 2)) * 128 + 124 + (row & 3)) * 128 : O_NKP + ((size_t)(L * 8 + (row >> 11)) * 128 + ((row & 2047) - 1920)) * 128;
;                         if (wr_out) { float* ko = out + kofs + wc * 64 + fq * 8; gst<f32x4>(ko, o1a); gst<f32x4>(ko + 4, o1b); gst<f32x4>(ko + 32, o2a); gst<f32x4>(ko + 36, o2b); }
.Lme_kvn_k_4:
	v_cvt_pk_bf16_f32 v60, v234, v235
	v_cvt_pk_bf16_f32 v61, v236, v237
	v_cvt_pk_bf16_f32 v62, v238, v239
	v_cvt_pk_bf16_f32 v63, v240, v241
	global_store_dwordx4 v215, v[60:63], s[16:17]
	v_cvt_pk_bf16_f32 v52, v104, v105
	v_cvt_pk_bf16_f32 v53, v106, v107
	v_cvt_pk_bf16_f32 v54, v108, v109
	v_cvt_pk_bf16_f32 v55, v110, v111
	global_store_dwordx4 v215, v[52:55], s[16:17] offset:64
	s_add_u32 s16, s16, 0x1000
	s_addc_u32 s17, s17, 0
	s_cmp_eq_u32 s9, 1
	s_cselect_b32 s5, 0x40000, 0
	s_cmp_eq_u32 s9, 2
	s_cselect_b32 s5, 0x2000, s5
	s_add_u32 s18, s18, s5
	s_addc_u32 s19, s19, 0
	v_pk_mul_f32 v[44:45], v[44:45], v[186:187] op_sel_hi:[1,0]
	v_pk_mul_f32 v[46:47], v[46:47], v[186:187] op_sel_hi:[1,0]
	v_pk_mul_f32 v[40:41], v[40:41], v[186:187] op_sel_hi:[1,0]
	v_pk_mul_f32 v[42:43], v[42:43], v[186:187] op_sel_hi:[1,0]
	v_pk_mul_f32 v[36:37], v[36:37], v[186:187] op_sel_hi:[1,0]
	v_pk_mul_f32 v[38:39], v[38:39], v[186:187] op_sel_hi:[1,0]
	v_pk_mul_f32 v[32:33], v[32:33], v[186:187] op_sel_hi:[1,0]
	v_pk_mul_f32 v[34:35], v[34:35], v[186:187] op_sel_hi:[1,0]
	s_waitcnt vmcnt(14)
	v_pk_mul_f32 v[234:235], v[36:37], v[226:227]
	v_pk_mul_f32 v[236:237], v[38:39], v[228:229]
	v_pk_mul_f32 v[238:239], v[32:33], v[230:231]
	v_pk_mul_f32 v[240:241], v[34:35], v[232:233]
	v_pk_fma_f32 v[234:235], v[44:45], v[218:219], v[234:235] neg_lo:[0,0,1] neg_hi:[0,0,1]
	v_pk_fma_f32 v[236:237], v[46:47], v[220:221], v[236:237] neg_lo:[0,0,1] neg_hi:[0,0,1]
	v_pk_fma_f32 v[238:239], v[40:41], v[222:223], v[238:239] neg_lo:[0,0,1] neg_hi:[0,0,1]
	v_pk_fma_f32 v[240:241], v[42:43], v[224:225], v[240:241] neg_lo:[0,0,1] neg_hi:[0,0,1]
	v_pk_mul_f32 v[226:227], v[44:45], v[226:227]
	v_pk_mul_f32 v[228:229], v[46:47], v[228:229]
	v_pk_mul_f32 v[230:231], v[40:41], v[230:231]
	v_pk_mul_f32 v[232:233], v[42:43], v[232:233]
	v_pk_fma_f32 v[226:227], v[36:37], v[218:219], v[226:227]
	v_pk_fma_f32 v[228:229], v[38:39], v[220:221], v[228:229]
	v_pk_fma_f32 v[230:231], v[32:33], v[222:223], v[230:231]
	v_pk_fma_f32 v[232:233], v[34:35], v[224:225], v[232:233]
	s_cmp_eq_u32 s9, 1
	s_cbranch_scc1 .Lme_kvs_k_5
	s_cmp_eq_u32 s9, 2
	s_cbranch_scc0 .Lme_kvn_k_5

; __device__ __forceinline__ u32x4 pk8(f32x4 a, f32x4 b) { u32x4 w; w.x = pk2(a[0], a[1]); w.y = pk2(a[2], a[3]); w.z = pk2(b[0], b[1]); w.w = pk2(b[2], b[3]); return w; }
;     __device__ __forceinline__ void operator()(const f32x4 (&acc)[2][2][4][2], const pg8::Unit& u, int wr, int wc, int fr_, int fq_) const {
;     ...
;                 const int k = it - 2, ai = k >> 2, m = k & 3, row = row0 + ai * 128 + m * 16;
;                 float sq = (ld[k].ss[0] + ld[k].ss[1]) + (ld[k].ss[2] + ld[k].ss[3]); sq += __shfl_xor(sq, 16); sq += __shfl_xor(sq, 32);
;                 const float rs = __builtin_amdgcn_rsqf(sq * (1.f / 1024.f) + EPS);
;                 const f32x4 a0 = acc[ai][0][m][0] * rs, a1 = acc[ai][0][m][1] * rs, b0 = acc[ai][1][m][0] * rs, b1 = acc[ai][1][m][1] * rs;
;                 if (rope) {
;                     const f32x4 c0 = ld[k].c0, c1 = ld[k].c1, s0 = ld[k].s0, s1 = ld[k].s1;
;                     f32x4 o1a = a0 * c0 - b0 * s0, o1b = a1 * c1 - b1 * s1, o2a = b0 * c0 + a0 * s0, o2b = b1 * c1 + a1 * s1;
;                     if (pn < 2) {
;                         o1a *= QS; o1b *= QS; o2a *= QS; o2b *= QS;
;                         bf16_t* q = Q + (size_t)row * 512 + (4 * pn + wc) * 64 + fq * 8;
;                         gst<u32x4>(q, pk8(o1a, o1b)); gst<u32x4>(q + 32, pk8(o2a, o2b));
;                     } else {
;                         bf16_t* kk = K + (size_t)row * 128 + wc * 64 + fq * 8;
;                         gst<u32x4>(kk, pk8(o1a, o1b)); gst<u32x4>(kk + 32, pk8(o2a, o2b));
;                         const bool smp = row >= NPR; const bool wr_out = smp || (row & 2047) >= 1920;
;                         const size_t kofs = smp ? O_NKS + ((size_t)(L * 128 + ((row - NPR) >> 2)) * 128 + 124 + (row & 3)) * 128 : O_NKP + ((size_t)(L * 8 + (row >> 11)) * 128 + ((row & 2047) - 1920)) * 128;
;                         if (wr_out) { float* ko = out + kofs + wc * 64 + fq * 8; gst<f32x4>(ko, o1a); gst<f32x4>(ko + 4, o1b); gst<f32x4>(ko + 32, o2a); gst<f32x4>(ko + 36, o2b); }
.Lme_kvn_k_5:
	v_cvt_pk_bf16_f32 v44, v234, v235
	v_cvt_pk_bf16_f32 v45, v236, v237
	v_cvt_pk_bf16_f32 v46, v238, v239
	v_cvt_pk_bf16_f32 v47, v240, v241
	global_store_dwordx4 v215, v[44:47], s[16:17]
	v_cvt_pk_bf16_f32 v36, v226, v227
	v_cvt_pk_bf16_f32 v37, v228, v229
	v_cvt_pk_bf16_f32 v38, v230, v231
	v_cvt_pk_bf16_f32 v39, v232, v233
	global_store_dwordx4 v215, v[36:39], s[16:17] offset:64
	s_add_u32 s16, s16, 0x1000
	s_addc_u32 s17, s17, 0
	s_cmp_eq_u32 s9, 1
	s_cselect_b32 s5, 0x40000, 0
	s_cmp_eq_u32 s9, 2
	s_cselect_b32 s5, 0x2000, s5
	s_add_u32 s18, s18, s5
	s_addc_u32 s19, s19, 0
	v_pk_mul_f32 v[28:29], v[28:29], v[188:189] op_sel_hi:[1,0]
	v_pk_mul_f32 v[30:31], v[30:31], v[188:189] op_sel_hi:[1,0]
	v_pk_mul_f32 v[24:25], v[24:25], v[188:189] op_sel_hi:[1,0]
	v_pk_mul_f32 v[26:27], v[26:27], v[188:189] op_sel_hi:[1,0]
	v_pk_mul_f32 v[20:21], v[20:21], v[188:189] op_sel_hi:[1,0]
	v_pk_mul_f32 v[22:23], v[22:23], v[188:189] op_sel_hi:[1,0]
	v_pk_mul_f32 v[16:17], v[16:17], v[188:189] op_sel_hi:[1,0]
	v_pk_mul_f32 v[18:19], v[18:19], v[188:189] op_sel_hi:[1,0]
	s_waitcnt vmcnt(10)
	v_pk_mul_f32 v[234:235], v[20:21], v[152:153]
	v_pk_mul_f32 v[236:237], v[22:23], v[154:155]
	v_pk_mul_f32 v[238:239], v[16:17], v[156:157]
	v_pk_mul_f32 v[240:241], v[18:19], v[158:159]
	v_pk_fma_f32 v[234:235], v[28:29], v[144:145], v[234:235] neg_lo:[0,0,1] neg_hi:[0,0,1]
	v_pk_fma_f32 v[236:237], v[30:31], v[146:147], v[236:237] neg_lo:[0,0,1] neg_hi:[0,0,1]
	v_pk_fma_f32 v[238:239], v[24:25], v[148:149], v[238:239] neg_lo:[0,0,1] neg_hi:[0,0,1]
	v_pk_fma_f32 v[240:241], v[26:27], v[150:151], v[240:241] neg_lo:[0,0,1] neg_hi:[0,0,1]
	v_pk_mul_f32 v[152:153], v[28:29], v[152:153]
	v_pk_mul_f32 v[154:155], v[30:31], v[154:155]
	v_pk_mul_f32 v[156:157], v[24:25], v[156:157]
	v_pk_mul_f32 v[158:159], v[26:27], v[158:159]
	v_pk_fma_f32 v[152:153], v[20:21], v[144:145], v[152:153]
	v_pk_fma_f32 v[154:155], v[22:23], v[146:147], v[154:155]
	v_pk_fma_f32 v[156:157], v[16:17], v[148:149], v[156:157]
	v_pk_fma_f32 v[158:159], v[18:19], v[150:151], v[158:159]
	s_cmp_eq_u32 s9, 1
	s_cbranch_scc1 .Lme_kvs_k_6
	s_cmp_eq_u32 s9, 2
	s_cbranch_scc0 .Lme_kvn_k_6

; __device__ __forceinline__ u32x4 pk8(f32x4 a, f32x4 b) { u32x4 w; w.x = pk2(a[0], a[1]); w.y = pk2(a[2], a[3]); w.z = pk2(b[0], b[1]); w.w = pk2(b[2], b[3]); return w; }
;     __device__ __forceinline__ void operator()(const f32x4 (&acc)[2][2][4][2], const pg8::Unit& u, int wr, int wc, int fr_, int fq_) const {
;     ...
;                 const int k = it - 2, ai = k >> 2, m = k & 3, row = row0 + ai * 128 + m * 16;
;                 float sq = (ld[k].ss[0] + ld[k].ss[1]) + (ld[k].ss[2] + ld[k].ss[3]); sq += __shfl_xor(sq, 16); sq += __shfl_xor(sq, 32);
;                 const float rs = __builtin_amdgcn_rsqf(sq * (1.f / 1024.f) + EPS);
;                 const f32x4 a0 = acc[ai][0][m][0] * rs, a1 = acc[ai][0][m][1] * rs, b0 = acc[ai][1][m][0] * rs, b1 = acc[ai][1][m][1] * rs;
;                 if (rope) {
;                     const f32x4 c0 = ld[k].c0, c1 = ld[k].c1, s0 = ld[k].s0, s1 = ld[k].s1;
;                     f32x4 o1a = a0 * c0 - b0 * s0, o1b = a1 * c1 - b1 * s1, o2a = b0 * c0 + a0 * s0, o2b = b1 * c1 + a1 * s1;
;                     if (pn < 2) {
;                         o1a *= QS; o1b *= QS; o2a *= QS; o2b *= QS;
;                         bf16_t* q = Q + (size_t)row * 512 + (4 * pn + wc) * 64 + fq * 8;
;                         gst<u32x4>(q, pk8(o1a, o1b)); gst<u32x4>(q + 32, pk8(o2a, o2b));
;                     } else {
;                         bf16_t* kk = K + (size_t)row * 128 + wc * 64 + fq * 8;
;                         gst<u32x4>(kk, pk8(o1a, o1b)); gst<u32x4>(kk + 32, pk8(o2a, o2b));
;                         const bool smp = row >= NPR; const bool wr_out = smp || (row & 2047) >= 1920;
;                         const size_t kofs = smp ? O_NKS + ((size_t)(L * 128 + ((row - NPR) >> 2)) * 128 + 124 + (row & 3)) * 128 : O_NKP + ((size_t)(L * 8 + (row >> 11)) * 128 + ((row & 2047) - 1920)) * 128;
;                         if (wr_out) { float* ko = out + kofs + wc * 64 + fq * 8; gst<f32x4>(ko, o1a); gst<f32x4>(ko + 4, o1b); gst<f32x4>(ko + 32, o2a); gst<f32x4>(ko + 36, o2b); }
.Lme_kvn_k_6:
	v_cvt_pk_bf16_f32 v28, v234, v235
	v_cvt_pk_bf16_f32 v29, v236, v237
	v_cvt_pk_bf16_f32 v30, v238, v239
	v_cvt_pk_bf16_f32 v31, v240, v241
	global_store_dwordx4 v215, v[28:31], s[16:17]
	v_cvt_pk_bf16_f32 v20, v152, v153
	v_cvt_pk_bf16_f32 v21, v154, v155
	v_cvt_pk_bf16_f32 v22, v156, v157
	v_cvt_pk_bf16_f32 v23, v158, v159
	global_store_dwordx4 v215, v[20:23], s[16:17] offset:64
	s_add_u32 s16, s16, 0x1000
	s_addc_u32 s17, s17, 0
	s_cmp_eq_u32 s9, 1
	s_cselect_b32 s5, 0x40000, 0
	s_cmp_eq_u32 s9, 2
	s_cselect_b32 s5, 0x2000, s5
	s_add_u32 s18, s18, s5
	s_addc_u32 s19, s19, 0
	v_pk_mul_f32 v[12:13], v[12:13], v[190:191] op_sel_hi:[1,0]
	v_pk_mul_f32 v[14:15], v[14:15], v[190:191] op_sel_hi:[1,0]
	v_pk_mul_f32 v[8:9], v[8:9], v[190:191] op_sel_hi:[1,0]
	v_pk_mul_f32 v[10:11], v[10:11], v[190:191] op_sel_hi:[1,0]
	v_pk_mul_f32 v[4:5], v[4:5], v[190:191] op_sel_hi:[1,0]
	v_pk_mul_f32 v[6:7], v[6:7], v[190:191] op_sel_hi:[1,0]
	v_pk_mul_f32 v[0:1], v[0:1], v[190:191] op_sel_hi:[1,0]
	v_pk_mul_f32 v[2:3], v[2:3], v[190:191] op_sel_hi:[1,0]
	s_waitcnt vmcnt(6)
	v_pk_mul_f32 v[234:235], v[4:5], v[168:169]
	v_pk_mul_f32 v[236:237], v[6:7], v[170:171]
	v_pk_mul_f32 v[238:239], v[0:1], v[172:173]
	v_pk_mul_f32 v[240:241], v[2:3], v[174:175]
	v_pk_fma_f32 v[234:235], v[12:13], v[160:161], v[234:235] neg_lo:[0,0,1] neg_hi:[0,0,1]
	v_pk_fma_f32 v[236:237], v[14:15], v[162:163], v[236:237] neg_lo:[0,0,1] neg_hi:[0,0,1]
	v_pk_fma_f32 v[238:239], v[8:9], v[164:165], v[238:239] neg_lo:[0,0,1] neg_hi:[0,0,1]
	v_pk_fma_f32 v[240:241], v[10:11], v[166:167], v[240:241] neg_lo:[0,0,1] neg_hi:[0,0,1]
	v_pk_mul_f32 v[168:169], v[12:13], v[168:169]
	v_pk_mul_f32 v[170:171], v[14:15], v[170:171]
	v_pk_mul_f32 v[172:173], v[8:9], v[172:173]
	v_pk_mul_f32 v[174:175], v[10:11], v[174:175]
	v_pk_fma_f32 v[168:169], v[4:5], v[160:161], v[168:169]
	v_pk_fma_f32 v[170:171], v[6:7], v[162:163], v[170:171]
	v_pk_fma_f32 v[172:173], v[0:1], v[164:165], v[172:173]
	v_pk_fma_f32 v[174:175], v[2:3], v[166:167], v[174:175]
	s_cmp_eq_u32 s9, 1
	s_cbranch_scc1 .Lme_kvs_k_7
	s_cmp_eq_u32 s9, 2
	s_cbranch_scc0 .Lme_kvn_k_7

; __device__ __forceinline__ u32x4 pk8(f32x4 a, f32x4 b) { u32x4 w; w.x = pk2(a[0], a[1]); w.y = pk2(a[2], a[3]); w.z = pk2(b[0], b[1]); w.w = pk2(b[2], b[3]); return w; }
;     __device__ __forceinline__ void operator()(const f32x4 (&acc)[2][2][4][2], const pg8::Unit& u, int wr, int wc, int fr_, int fq_) const {
;     ...
;                         bf16_t* kk = K + (size_t)row * 128 + wc * 64 + fq * 8;
;                         gst<u32x4>(kk, pk8(o1a, o1b)); gst<u32x4>(kk + 32, pk8(o2a, o2b));
;                         const bool smp = row >= NPR; const bool wr_out = smp || (row & 2047) >= 1920;
;                         const size_t kofs = smp ? O_NKS + ((size_t)(L * 128 + ((row - NPR) >> 2)) * 128 + 124 + (row & 3)) * 128 : O_NKP + ((size_t)(L * 8 + (row >> 11)) * 128 + ((row & 2047) - 1920)) * 128;
;                         if (wr_out) { float* ko = out + kofs + wc * 64 + fq * 8; gst<f32x4>(ko, o1a); gst<f32x4>(ko + 4, o1b); gst<f32x4>(ko + 32, o2a); gst<f32x4>(ko + 36, o2b); }
;                     }
;                 } else if (pn == 2) {
;                     bf16_t* v = V + (size_t)row * 128 + (wc - 2) * 32 + fq * 8;
;                     gst<u32x4>(v, pk8(a0, a1)); gst<u32x4>(v + 64, pk8(b0, b1));
;                     const bool smp = row >= NPR; const bool wr_out = smp || (row & 2047) >= 1920;
;                     const size_t vofs = smp ? O_NVS + ((size_t)(L * 128 + ((row - NPR) >> 2)) * 128 + 124 + (row & 3)) * 128 : O_NVP + ((size_t)(L * 8 + (row >> 11)) * 128 + ((row & 2047) - 1920)) * 128;
;                     if (wr_out) { float* vo = out + vofs + (wc - 2) * 32 + fq * 8; gst<f32x4>(vo, a0); gst<f32x4>(vo + 4, a1); gst<f32x4>(vo + 64, b0); gst<f32x4>(vo + 68, b1); }
.Lme_kvn_k_7:
	v_cvt_pk_bf16_f32 v12, v234, v235
	v_cvt_pk_bf16_f32 v13, v236, v237
	v_cvt_pk_bf16_f32 v14, v238, v239
	v_cvt_pk_bf16_f32 v15, v240, v241
	global_store_dwordx4 v215, v[12:15], s[16:17]
	v_cvt_pk_bf16_f32 v4, v168, v169
	v_cvt_pk_bf16_f32 v5, v170, v171
	v_cvt_pk_bf16_f32 v6, v172, v173
	v_cvt_pk_bf16_f32 v7, v174, v175
	global_store_dwordx4 v215, v[4:7], s[16:17] offset:64
	s_branch .LBB0_580
.Lme_vpath:
	s_mov_b32 s9, 0
	s_cmp_gt_i32 s4, 63
	s_cbranch_scc1 .Lme_kvsmp_v
	s_and_b32 s5, s4, 7
	s_cmp_eq_u32 s5, 7
	s_cbranch_scc0 .Lme_kvfd_v
	s_mov_b32 s9, 2
	v_and_b32_e32 v216, 15, v248
	v_lshlrev_b32_e32 v216, 9, v216
	v_lshl_add_u32 v216, v211, 5, v216
	s_lshl_b32 s5, s20, 3
	s_lshr_b32 s18, s4, 3
	s_add_i32 s5, s5, s18
	s_lshl_b32 s5, s5, 16
	s_lshl_b32 s18, s89, 9
	s_add_i32 s5, s5, s18
	s_add_u32 s5, s5, 0x4400000
	s_branch .Lme_kvfb_v
.Lme_kvsmp_v:
	s_mov_b32 s9, 1
	v_and_b32_e32 v216, 15, v248
	v_lshrrev_b32_e32 v217, 2, v216
	v_and_b32_e32 v216, 3, v216
	v_lshlrev_b32_e32 v216, 9, v216
	v_lshl_add_u32 v216, v217, 16, v216
	v_lshl_add_u32 v216, v211, 5, v216
	s_add_i32 s5, s4, -64
	s_lshl_b32 s5, s5, 6
	s_lshr_b32 s18, s89, 2
	s_add_i32 s5, s5, s18
	s_lshl_b32 s5, s5, 16
	s_lshl_b32 s18, s20, 23
	s_add_i32 s5, s5, s18
	s_add_u32 s5, s5, 0x662f800
.Lme_kvfb_v:
	s_add_i32 s18, s93, 0xffffff80
	s_lshl_b32 s18, s18, 1
	s_add_i32 s5, s5, s18
	s_add_u32 s18, s28, s5
	s_addc_u32 s19, s29, 0
.Lme_kvfd_v:
	v_pk_mul_f32 v[132:133], v[132:133], v[176:177] op_sel_hi:[1,0]
	v_pk_mul_f32 v[134:135], v[134:135], v[176:177] op_sel_hi:[1,0]
	v_pk_mul_f32 v[128:129], v[128:129], v[176:177] op_sel_hi:[1,0]
	v_pk_mul_f32 v[130:131], v[130:131], v[176:177] op_sel_hi:[1,0]
	v_pk_mul_f32 v[116:117], v[116:117], v[176:177] op_sel_hi:[1,0]
	v_pk_mul_f32 v[118:119], v[118:119], v[176:177] op_sel_hi:[1,0]
	v_pk_mul_f32 v[112:113], v[112:113], v[176:177] op_sel_hi:[1,0]
	v_pk_mul_f32 v[114:115], v[114:115], v[176:177] op_sel_hi:[1,0]
	s_nop 0
	s_cmp_eq_u32 s9, 1
	s_cbranch_scc0 .Lme_kvn_v_0
.Lme_kvs_v_0:
	global_store_dwordx4 v216, v[132:135], s[18:19]
	global_store_dwordx4 v216, v[128:131], s[18:19] offset:16
	global_store_dwordx4 v216, v[116:119], s[18:19] offset:256
	global_store_dwordx4 v216, v[112:115], s[18:19] offset:272
.Lme_kvn_v_0:
	v_cvt_pk_bf16_f32 v104, v132, v133
	v_cvt_pk_bf16_f32 v105, v134, v135
	v_cvt_pk_bf16_f32 v106, v128, v129
	v_cvt_pk_bf16_f32 v107, v130, v131
	global_store_dwordx4 v215, v[104:107], s[16:17]
	v_cvt_pk_bf16_f32 v218, v116, v117
	v_cvt_pk_bf16_f32 v219, v118, v119
	v_cvt_pk_bf16_f32 v220, v112, v113
	v_cvt_pk_bf16_f32 v221, v114, v115
	global_store_dwordx4 v215, v[218:221], s[16:17] offset:128
	s_add_u32 s16, s16, 0x1000
	s_addc_u32 s17, s17, 0
	s_cmp_eq_u32 s9, 1
	s_cselect_b32 s5, 0x40000, 0
	s_add_u32 s18, s18, s5
	s_addc_u32 s19, s19, 0
	v_pk_mul_f32 v[140:141], v[140:141], v[178:179] op_sel_hi:[1,0]
	v_pk_mul_f32 v[142:143], v[142:143], v[178:179] op_sel_hi:[1,0]
	v_pk_mul_f32 v[136:137], v[136:137], v[178:179] op_sel_hi:[1,0]
	v_pk_mul_f32 v[138:139], v[138:139], v[178:179] op_sel_hi:[1,0]
	v_pk_mul_f32 v[124:125], v[124:125], v[178:179] op_sel_hi:[1,0]
	v_pk_mul_f32 v[126:127], v[126:127], v[178:179] op_sel_hi:[1,0]
	v_pk_mul_f32 v[120:121], v[120:121], v[178:179] op_sel_hi:[1,0]
	v_pk_mul_f32 v[122:123], v[122:123], v[178:179] op_sel_hi:[1,0]
	s_nop 0
	s_cmp_eq_u32 s9, 1
	s_cbranch_scc0 .Lme_kvn_v_1
.Lme_kvs_v_1:
	global_store_dwordx4 v216, v[140:143], s[18:19]
	global_store_dwordx4 v216, v[136:139], s[18:19] offset:16
	global_store_dwordx4 v216, v[124:127], s[18:19] offset:256
	global_store_dwordx4 v216, v[120:123], s[18:19] offset:272
.Lme_kvn_v_1:
	v_cvt_pk_bf16_f32 v108, v140, v141
	v_cvt_pk_bf16_f32 v109, v142, v143
	v_cvt_pk_bf16_f32 v110, v136, v137
	v_cvt_pk_bf16_f32 v111, v138, v139
	global_store_dwordx4 v215, v[108:111], s[16:17]
	v_cvt_pk_bf16_f32 v222, v124, v125
	v_cvt_pk_bf16_f32 v223, v126, v127
	v_cvt_pk_bf16_f32 v224, v120, v121
	v_cvt_pk_bf16_f32 v225, v122, v123
	global_store_dwordx4 v215, v[222:225], s[16:17] offset:128
	s_add_u32 s16, s16, 0x1000
	s_addc_u32 s17, s17, 0
	s_cmp_eq_u32 s9, 1
	s_cselect_b32 s5, 0x40000, 0
	s_add_u32 s18, s18, s5
	s_addc_u32 s19, s19, 0
	v_pk_mul_f32 v[92:93], v[92:93], v[180:181] op_sel_hi:[1,0]
	v_pk_mul_f32 v[94:95], v[94:95], v[180:181] op_sel_hi:[1,0]
	v_pk_mul_f32 v[88:89], v[88:89], v[180:181] op_sel_hi:[1,0]
	v_pk_mul_f32 v[90:91], v[90:91], v[180:181] op_sel_hi:[1,0]
	v_pk_mul_f32 v[84:85], v[84:85], v[180:181] op_sel_hi:[1,0]
	v_pk_mul_f32 v[86:87], v[86:87], v[180:181] op_sel_hi:[1,0]
	v_pk_mul_f32 v[80:81], v[80:81], v[180:181] op_sel_hi:[1,0]
	v_pk_mul_f32 v[82:83], v[82:83], v[180:181] op_sel_hi:[1,0]
	s_nop 0
	s_cmp_eq_u32 s9, 1
	s_cbranch_scc0 .Lme_kvn_v_2
.Lme_kvs_v_2:
	global_store_dwordx4 v216, v[92:95], s[18:19]
	global_store_dwordx4 v216, v[88:91], s[18:19] offset:16
	global_store_dwordx4 v216, v[84:87], s[18:19] offset:256
	global_store_dwordx4 v216, v[80:83], s[18:19] offset:272
.Lme_kvn_v_2:
	v_cvt_pk_bf16_f32 v104, v92, v93
	v_cvt_pk_bf16_f32 v105, v94, v95
	v_cvt_pk_bf16_f32 v106, v88, v89
	v_cvt_pk_bf16_f32 v107, v90, v91
	global_store_dwordx4 v215, v[104:107], s[16:17]
	v_cvt_pk_bf16_f32 v218, v84, v85
	v_cvt_pk_bf16_f32 v219, v86, v87
	v_cvt_pk_bf16_f32 v220, v80, v81
	v_cvt_pk_bf16_f32 v221, v82, v83
	global_store_dwordx4 v215, v[218:221], s[16:17] offset:128
	s_add_u32 s16, s16, 0x1000
	s_addc_u32 s17, s17, 0
	s_cmp_eq_u32 s9, 1
	s_cselect_b32 s5, 0x40000, 0
	s_add_u32 s18, s18, s5
	s_addc_u32 s19, s19, 0
	v_pk_mul_f32 v[76:77], v[76:77], v[182:183] op_sel_hi:[1,0]
	v_pk_mul_f32 v[78:79], v[78:79], v[182:183] op_sel_hi:[1,0]
	v_pk_mul_f32 v[72:73], v[72:73], v[182:183] op_sel_hi:[1,0]
	v_pk_mul_f32 v[74:75], v[74:75], v[182:183] op_sel_hi:[1,0]
	v_pk_mul_f32 v[68:69], v[68:69], v[182:183] op_sel_hi:[1,0]
	v_pk_mul_f32 v[70:71], v[70:71], v[182:183] op_sel_hi:[1,0]
	v_pk_mul_f32 v[64:65], v[64:65], v[182:183] op_sel_hi:[1,0]
	v_pk_mul_f32 v[66:67], v[66:67], v[182:183] op_sel_hi:[1,0]
	s_nop 0
	s_cmp_eq_u32 s9, 1
	s_cbranch_scc0 .Lme_kvn_v_3
; __device__ __forceinline__ u32x4 pk8(f32x4 a, f32x4 b) { u32x4 w; w.x = pk2(a[0], a[1]); w.y = pk2(a[2], a[3]); w.z = pk2(b[0], b[1]); w.w = pk2(b[2], b[3]); return w; }
;     __device__ __forceinline__ void operator()(const f32x4 (&acc)[2][2][4][2], const pg8::Unit& u, int wr, int wc, int fr_, int fq_) const {
;     ...
;                 } else if (pn == 2) {
;                     bf16_t* v = V + (size_t)row * 128 + (wc - 2) * 32 + fq * 8;
;                     gst<u32x4>(v, pk8(a0, a1)); gst<u32x4>(v + 64, pk8(b0, b1));
;                     const bool smp = row >= NPR; const bool wr_out = smp || (row & 2047) >= 1920;
;                     const size_t vofs = smp ? O_NVS + ((size_t)(L * 128 + ((row - NPR) >> 2)) * 128 + 124 + (row & 3)) * 128 : O_NVP + ((size_t)(L * 8 + (row >> 11)) * 128 + ((row & 2047) - 1920)) * 128;
;                     if (wr_out) { float* vo = out + vofs + (wc - 2) * 32 + fq * 8; gst<f32x4>(vo, a0); gst<f32x4>(vo + 4, a1); gst<f32x4>(vo + 64, b0); gst<f32x4>(vo + 68, b1); }
.Lme_kvs_v_3:
	global_store_dwordx4 v216, v[76:79], s[18:19]
	global_store_dwordx4 v216, v[72:75], s[18:19] offset:16
	global_store_dwordx4 v216, v[68:71], s[18:19] offset:256
	global_store_dwordx4 v216, v[64:67], s[18:19] offset:272
.Lme_kvn_v_3:
	v_cvt_pk_bf16_f32 v108, v76, v77
	v_cvt_pk_bf16_f32 v109, v78, v79
	v_cvt_pk_bf16_f32 v110, v72, v73
	v_cvt_pk_bf16_f32 v111, v74, v75
	global_store_dwordx4 v215, v[108:111], s[16:17]
	v_cvt_pk_bf16_f32 v222, v68, v69
	v_cvt_pk_bf16_f32 v223, v70, v71
	v_cvt_pk_bf16_f32 v224, v64, v65
	v_cvt_pk_bf16_f32 v225, v66, v67
	global_store_dwordx4 v215, v[222:225], s[16:17] offset:128
	s_add_u32 s16, s16, 0x5000
	s_addc_u32 s17, s17, 0
	s_cmp_eq_u32 s9, 1
	s_cselect_b32 s5, 0x140000, 0
	s_add_u32 s18, s18, s5
	s_addc_u32 s19, s19, 0
	v_pk_mul_f32 v[60:61], v[60:61], v[184:185] op_sel_hi:[1,0]
	v_pk_mul_f32 v[62:63], v[62:63], v[184:185] op_sel_hi:[1,0]
	v_pk_mul_f32 v[56:57], v[56:57], v[184:185] op_sel_hi:[1,0]
	v_pk_mul_f32 v[58:59], v[58:59], v[184:185] op_sel_hi:[1,0]
	v_pk_mul_f32 v[52:53], v[52:53], v[184:185] op_sel_hi:[1,0]
	v_pk_mul_f32 v[54:55], v[54:55], v[184:185] op_sel_hi:[1,0]
	v_pk_mul_f32 v[48:49], v[48:49], v[184:185] op_sel_hi:[1,0]
	v_pk_mul_f32 v[50:51], v[50:51], v[184:185] op_sel_hi:[1,0]
	s_nop 0
	s_cmp_eq_u32 s9, 1
	s_cbranch_scc1 .Lme_kvs_v_4
	s_cmp_eq_u32 s9, 2
	s_cbranch_scc0 .Lme_kvn_v_4
.Lme_kvs_v_4:
	global_store_dwordx4 v216, v[60:63], s[18:19]
	global_store_dwordx4 v216, v[56:59], s[18:19] offset:16
	global_store_dwordx4 v216, v[52:55], s[18:19] offset:256
	global_store_dwordx4 v216, v[48:51], s[18:19] offset:272
.Lme_kvn_v_4:
	v_cvt_pk_bf16_f32 v104, v60, v61
	v_cvt_pk_bf16_f32 v105, v62, v63
	v_cvt_pk_bf16_f32 v106, v56, v57
	v_cvt_pk_bf16_f32 v107, v58, v59
	global_store_dwordx4 v215, v[104:107], s[16:17]
	v_cvt_pk_bf16_f32 v218, v52, v53
	v_cvt_pk_bf16_f32 v219, v54, v55
	v_cvt_pk_bf16_f32 v220, v48, v49
	v_cvt_pk_bf16_f32 v221, v50, v51
	global_store_dwordx4 v215, v[218:221], s[16:17] offset:128
	s_add_u32 s16, s16, 0x1000
	s_addc_u32 s17, s17, 0
	s_cmp_eq_u32 s9, 1
	s_cselect_b32 s5, 0x40000, 0
	s_cmp_eq_u32 s9, 2
	s_cselect_b32 s5, 0x2000, s5
	s_add_u32 s18, s18, s5
	s_addc_u32 s19, s19, 0
	v_pk_mul_f32 v[44:45], v[44:45], v[186:187] op_sel_hi:[1,0]
	v_pk_mul_f32 v[46:47], v[46:47], v[186:187] op_sel_hi:[1,0]
	v_pk_mul_f32 v[40:41], v[40:41], v[186:187] op_sel_hi:[1,0]
	v_pk_mul_f32 v[42:43], v[42:43], v[186:187] op_sel_hi:[1,0]
	v_pk_mul_f32 v[36:37], v[36:37], v[186:187] op_sel_hi:[1,0]
	v_pk_mul_f32 v[38:39], v[38:39], v[186:187] op_sel_hi:[1,0]
	v_pk_mul_f32 v[32:33], v[32:33], v[186:187] op_sel_hi:[1,0]
	v_pk_mul_f32 v[34:35], v[34:35], v[186:187] op_sel_hi:[1,0]
	s_nop 0
	s_cmp_eq_u32 s9, 1
	s_cbranch_scc1 .Lme_kvs_v_5
	s_cmp_eq_u32 s9, 2
	s_cbranch_scc0 .Lme_kvn_v_5
.Lme_kvs_v_5:
	global_store_dwordx4 v216, v[44:47], s[18:19]
	global_store_dwordx4 v216, v[40:43], s[18:19] offset:16
	global_store_dwordx4 v216, v[36:39], s[18:19] offset:256
	global_store_dwordx4 v216, v[32:35], s[18:19] offset:272
.Lme_kvn_v_5:
	v_cvt_pk_bf16_f32 v108, v44, v45
	v_cvt_pk_bf16_f32 v109, v46, v47
	v_cvt_pk_bf16_f32 v110, v40, v41
	v_cvt_pk_bf16_f32 v111, v42, v43
	global_store_dwordx4 v215, v[108:111], s[16:17]
	v_cvt_pk_bf16_f32 v222, v36, v37
	v_cvt_pk_bf16_f32 v223, v38, v39
	v_cvt_pk_bf16_f32 v224, v32, v33
	v_cvt_pk_bf16_f32 v225, v34, v35
	global_store_dwordx4 v215, v[222:225], s[16:17] offset:128
	s_add_u32 s16, s16, 0x1000
	s_addc_u32 s17, s17, 0
	s_cmp_eq_u32 s9, 1
	s_cselect_b32 s5, 0x40000, 0
	s_cmp_eq_u32 s9, 2
	s_cselect_b32 s5, 0x2000, s5
	s_add_u32 s18, s18, s5
	s_addc_u32 s19, s19, 0
	v_pk_mul_f32 v[28:29], v[28:29], v[188:189] op_sel_hi:[1,0]
	v_pk_mul_f32 v[30:31], v[30:31], v[188:189] op_sel_hi:[1,0]
	v_pk_mul_f32 v[24:25], v[24:25], v[188:189] op_sel_hi:[1,0]
	v_pk_mul_f32 v[26:27], v[26:27], v[188:189] op_sel_hi:[1,0]
	v_pk_mul_f32 v[20:21], v[20:21], v[188:189] op_sel_hi:[1,0]
	v_pk_mul_f32 v[22:23], v[22:23], v[188:189] op_sel_hi:[1,0]
	v_pk_mul_f32 v[16:17], v[16:17], v[188:189] op_sel_hi:[1,0]
	v_pk_mul_f32 v[18:19], v[18:19], v[188:189] op_sel_hi:[1,0]
	s_nop 0
	s_cmp_eq_u32 s9, 1
	s_cbranch_scc1 .Lme_kvs_v_6
	s_cmp_eq_u32 s9, 2
	s_cbranch_scc0 .Lme_kvn_v_6
.Lme_kvs_v_6:
	global_store_dwordx4 v216, v[28:31], s[18:19]
	global_store_dwordx4 v216, v[24:27], s[18:19] offset:16
	global_store_dwordx4 v216, v[20:23], s[18:19] offset:256
	global_store_dwordx4 v216, v[16:19], s[18:19] offset:272
.Lme_kvn_v_6:
	v_cvt_pk_bf16_f32 v104, v28, v29
	v_cvt_pk_bf16_f32 v105, v30, v31
	v_cvt_pk_bf16_f32 v106, v24, v25
	v_cvt_pk_bf16_f32 v107, v26, v27
	global_store_dwordx4 v215, v[104:107], s[16:17]
	v_cvt_pk_bf16_f32 v218, v20, v21
	v_cvt_pk_bf16_f32 v219, v22, v23
	v_cvt_pk_bf16_f32 v220, v16, v17
	v_cvt_pk_bf16_f32 v221, v18, v19
	global_store_dwordx4 v215, v[218:221], s[16:17] offset:128
	s_add_u32 s16, s16, 0x1000
	s_addc_u32 s17, s17, 0
	s_cmp_eq_u32 s9, 1
	s_cselect_b32 s5, 0x40000, 0
	s_cmp_eq_u32 s9, 2
	s_cselect_b32 s5, 0x2000, s5
	s_add_u32 s18, s18, s5
	s_addc_u32 s19, s19, 0
	v_pk_mul_f32 v[12:13], v[12:13], v[190:191] op_sel_hi:[1,0]
	v_pk_mul_f32 v[14:15], v[14:15], v[190:191] op_sel_hi:[1,0]
	v_pk_mul_f32 v[8:9], v[8:9], v[190:191] op_sel_hi:[1,0]
	v_pk_mul_f32 v[10:11], v[10:11], v[190:191] op_sel_hi:[1,0]
	v_pk_mul_f32 v[4:5], v[4:5], v[190:191] op_sel_hi:[1,0]
	v_pk_mul_f32 v[6:7], v[6:7], v[190:191] op_sel_hi:[1,0]
	v_pk_mul_f32 v[0:1], v[0:1], v[190:191] op_sel_hi:[1,0]
	v_pk_mul_f32 v[2:3], v[2:3], v[190:191] op_sel_hi:[1,0]
	s_nop 0
	s_cmp_eq_u32 s9, 1
	s_cbranch_scc1 .Lme_kvs_v_7
	s_cmp_eq_u32 s9, 2
	s_cbranch_scc0 .Lme_kvn_v_7
.Lme_kvs_v_7:
	global_store_dwordx4 v216, v[12:15], s[18:19]
	global_store_dwordx4 v216, v[8:11], s[18:19] offset:16
	global_store_dwordx4 v216, v[4:7], s[18:19] offset:256
	global_store_dwordx4 v216, v[0:3], s[18:19] offset:272
.Lme_kvn_v_7:
	v_cvt_pk_bf16_f32 v108, v12, v13
	v_cvt_pk_bf16_f32 v109, v14, v15
	v_cvt_pk_bf16_f32 v110, v8, v9
	v_cvt_pk_bf16_f32 v111, v10, v11
	global_store_dwordx4 v215, v[108:111], s[16:17]
	v_cvt_pk_bf16_f32 v222, v4, v5
	v_cvt_pk_bf16_f32 v223, v6, v7
	v_cvt_pk_bf16_f32 v224, v0, v1
	v_cvt_pk_bf16_f32 v225, v2, v3
	global_store_dwordx4 v215, v[222:225], s[16:17] offset:128
	s_branch .LBB0_580
